# GEMM K-loop MFMA order variant V2 (same-accumulator k-steps adjacent)
# baseline (speedup 1.0000x reference)
; #define PG8_STAGE(bufoff, gbase, voff) do { _Pragma("unroll") for (int _i = 0; _i < 2; ++_i) \
;         __builtin_amdgcn_global_load_lds((const unsigned*)((const char*)(gbase) + (voff)[_i]), (PG8_LAS unsigned*)(lds + (bufoff) + ldsw + _i * 8192), 16, 0, 0); } while (0)
; #define PG8_LDA(dst, b, h) do { _Pragma("unroll") for (int m = 0; m < 4; ++m) _Pragma("unroll") for (int k = 0; k < 2; ++k) dst[m][k] = *(const PG8_LAS bf16x8*)(lds + PG8_SA(b, h) + aoff + m * 2048 + k * 1024); } while (0)
; #define PG8_LDB(dst, b, h) do { _Pragma("unroll") for (int n = 0; n < 2; ++n) _Pragma("unroll") for (int k = 0; k < 2; ++k) dst[n][k] = *(const PG8_LAS bf16x8*)(lds + PG8_SB(b, h) + boff + n * 2048 + k * 1024); } while (0)
; #define PG8_MMA(ai, bj, At, Bt) do { __builtin_amdgcn_s_setprio(1); _Pragma("unroll") for (int m = 0; m < 4; ++m) _Pragma("unroll") for (int n = 0; n < 2; ++n) _Pragma("unroll") for (int k = 0; k < 2; ++k) \
;         acc[ai][bj][m][n] = __builtin_amdgcn_mfma_f32_16x16x32_bf16(Bt[n][k], At[m][k], acc[ai][bj][m][n], 0, 0, 0); __builtin_amdgcn_s_setprio(0); } while (0)
; #define PG8_WAIT_V(n) asm volatile("s_waitcnt vmcnt(" #n ")" ::: "memory")
; #define PG8_WAIT_L(n) asm volatile("s_waitcnt lgkmcnt(" #n ")" ::: "memory")
; #define PG8_BAR __builtin_amdgcn_s_barrier()
; #define PG8_SCHED __builtin_amdgcn_sched_barrier(0)
; template <class Epi, class Sched, bool ALIGN_EPI = false, bool SP2 = false>
; __device__ __forceinline__ void gemm_phase(PG8_LAS unsigned char* lds, const Gemm g, const Sched& S, const Epi& E) {
;     ...
;         for (int t = 0; t < nt; t += 2) {
;             const bool last = (t == nt - 2);
;             const char* a1 = cA + (size_t)(t + 1) * kstep;
;             const char* a2 = last ? nA : cA + (size_t)(t + 2) * kstep; const char* b2 = last ? nB : cB + (size_t)(t + 2) * kstep;
;             const char* a3 = a2 + kstep; const char* b3 = b2 + kstep;
;             if (last && has_next) S.a_ready(nxt);
;             if constexpr (SP2) {
;             PG8_LDB(B0, 0, 0); PG8_LDB(B1, 0, 1); PG8_SCHED; PG8_LDA(At, 0, 0); PG8_STAGE(PG8_SA(1, 1), a1 + hstep, voffA);
;             PG8_WAIT_V(8); PG8_WAIT_L(0); PG8_BAR; PG8_MMA(0, 0, At, B0); PG8_MMA(0, 1, At, B1); PG8_BAR; PG8_SCHED;
;             PG8_LDA(At, 0, 1); PG8_STAGE(PG8_SB(0, 0), b2, voffB); PG8_STAGE(PG8_SB(0, 1), b2 + hstep, voffB); PG8_STAGE(PG8_SA(0, 0), a2, voffA);
.LBB0_132:
	s_add_u32 s18, s46, 0xfffc0080
	s_addc_u32 s38, s47, -1
	s_add_i32 s39, 0, 0x10000
	s_cmp_eq_u32 s85, 12
	s_cselect_b32 s81, s33, s38
	s_cselect_b32 s80, s73, s18
	v_add_u32_e32 v0, s39, v176
	s_cselect_b32 s45, s75, s84
	s_cselect_b32 s44, s82, s83
	s_add_i32 s18, 0, 0x14000
	ds_read_b128 v[144:147], v0
	ds_read_b128 v[148:151], v0 offset:1024
	ds_read_b128 v[152:155], v0 offset:2048
	ds_read_b128 v[156:159], v0 offset:3072
	v_add_u32_e32 v0, s18, v176
	ds_read_b128 v[160:163], v0
	ds_read_b128 v[164:167], v0 offset:1024
	ds_read_b128 v[168:171], v0 offset:2048
	ds_read_b128 v[172:175], v0 offset:3072
	v_lshl_add_u64 v[218:219], s[46:47], 0, v[140:141]
	s_add_i32 m0, s92, 0xc000
	ds_read_b128 v[180:183], v178
	ds_read_b128 v[184:187], v178 offset:1024
	ds_read_b128 v[188:191], v178 offset:2048
	ds_read_b128 v[192:195], v178 offset:3072
	ds_read_b128 v[202:205], v178 offset:4096
	ds_read_b128 v[206:209], v178 offset:5120
	ds_read_b128 v[210:213], v178 offset:6144
	ds_read_b128 v[214:217], v178 offset:7168
	global_load_lds_dwordx4 v[218:219], off
	v_lshl_add_u64 v[218:219], s[46:47], 0, v[142:143]
	s_add_i32 m0, s92, 0xe000
	s_nop 0
	global_load_lds_dwordx4 v[218:219], off
	s_waitcnt vmcnt(8)
	s_waitcnt lgkmcnt(0)
	s_barrier
	s_setprio 1
	s_waitcnt lgkmcnt(0)
	v_mfma_f32_16x16x32_bf16 v[118:121], v[144:147], v[180:183], v[118:121]
	v_mfma_f32_16x16x32_bf16 v[118:121], v[148:151], v[184:187], v[118:121]
	v_mfma_f32_16x16x32_bf16 v[114:117], v[152:155], v[180:183], v[114:117]
	v_mfma_f32_16x16x32_bf16 v[114:117], v[156:159], v[184:187], v[114:117]
	v_mfma_f32_16x16x32_bf16 v[126:129], v[160:163], v[180:183], v[126:129]
	v_mfma_f32_16x16x32_bf16 v[126:129], v[164:167], v[184:187], v[126:129]
	v_mfma_f32_16x16x32_bf16 v[122:125], v[168:171], v[180:183], v[122:125]
	v_mfma_f32_16x16x32_bf16 v[122:125], v[172:175], v[184:187], v[122:125]
	v_mfma_f32_16x16x32_bf16 v[102:105], v[144:147], v[188:191], v[102:105]
	v_mfma_f32_16x16x32_bf16 v[102:105], v[148:151], v[192:195], v[102:105]
	v_mfma_f32_16x16x32_bf16 v[98:101], v[152:155], v[188:191], v[98:101]
	v_mfma_f32_16x16x32_bf16 v[98:101], v[156:159], v[192:195], v[98:101]
	v_mfma_f32_16x16x32_bf16 v[110:113], v[160:163], v[188:191], v[110:113]
	v_mfma_f32_16x16x32_bf16 v[110:113], v[164:167], v[192:195], v[110:113]
	v_mfma_f32_16x16x32_bf16 v[106:109], v[168:171], v[188:191], v[106:109]
	v_mfma_f32_16x16x32_bf16 v[106:109], v[172:175], v[192:195], v[106:109]
	v_mfma_f32_16x16x32_bf16 v[86:89], v[144:147], v[202:205], v[86:89]
	v_mfma_f32_16x16x32_bf16 v[86:89], v[148:151], v[206:209], v[86:89]
	v_mfma_f32_16x16x32_bf16 v[82:85], v[152:155], v[202:205], v[82:85]
	v_mfma_f32_16x16x32_bf16 v[82:85], v[156:159], v[206:209], v[82:85]
	v_mfma_f32_16x16x32_bf16 v[94:97], v[160:163], v[202:205], v[94:97]
	v_mfma_f32_16x16x32_bf16 v[94:97], v[164:167], v[206:209], v[94:97]
	v_mfma_f32_16x16x32_bf16 v[90:93], v[168:171], v[202:205], v[90:93]
	v_mfma_f32_16x16x32_bf16 v[90:93], v[172:175], v[206:209], v[90:93]
	v_mfma_f32_16x16x32_bf16 v[70:73], v[144:147], v[210:213], v[70:73]
	v_mfma_f32_16x16x32_bf16 v[70:73], v[148:151], v[214:217], v[70:73]
	v_mfma_f32_16x16x32_bf16 v[66:69], v[152:155], v[210:213], v[66:69]
	v_mfma_f32_16x16x32_bf16 v[66:69], v[156:159], v[214:217], v[66:69]
	v_mfma_f32_16x16x32_bf16 v[78:81], v[160:163], v[210:213], v[78:81]
	v_mfma_f32_16x16x32_bf16 v[78:81], v[164:167], v[214:217], v[78:81]
	v_mfma_f32_16x16x32_bf16 v[74:77], v[168:171], v[210:213], v[74:77]
	v_mfma_f32_16x16x32_bf16 v[74:77], v[172:175], v[214:217], v[74:77]
	s_setprio 0
	s_barrier
	s_add_i32 s38, s39, s91
	v_lshl_add_u64 v[218:219], s[44:45], 0, v[134:135]
	s_mov_b32 m0, s38
	ds_read_b128 v[180:183], v178 offset:16384
	ds_read_b128 v[184:187], v178 offset:17408
	ds_read_b128 v[188:191], v178 offset:18432
	ds_read_b128 v[192:195], v178 offset:19456
	ds_read_b128 v[202:205], v178 offset:20480
	ds_read_b128 v[206:209], v178 offset:21504
	ds_read_b128 v[210:213], v178 offset:22528
	ds_read_b128 v[214:217], v178 offset:23552
	global_load_lds_dwordx4 v[218:219], off
	s_add_i32 m0, s38, 0x2000
	s_add_u32 s38, s44, 0x40000
	v_lshl_add_u64 v[220:221], s[44:45], 0, v[130:131]
	s_addc_u32 s39, s45, 0
	s_add_i32 s18, s18, s91
	global_load_lds_dwordx4 v[220:221], off
	v_lshl_add_u64 v[222:223], s[38:39], 0, v[134:135]
	s_mov_b32 m0, s18
	v_lshl_add_u64 v[224:225], s[80:81], 0, v[132:133]
	global_load_lds_dwordx4 v[222:223], off
	v_lshl_add_u64 v[222:223], s[38:39], 0, v[130:131]
	s_add_i32 m0, s18, 0x2000
	s_nop 0
	global_load_lds_dwordx4 v[222:223], off
	v_lshl_add_u64 v[222:223], s[80:81], 0, v[136:137]
	s_mov_b32 m0, s92
	s_nop 0
	global_load_lds_dwordx4 v[222:223], off
	s_mov_b32 m0, s93
	s_nop 0
	global_load_lds_dwordx4 v[224:225], off
	s_waitcnt vmcnt(8)
	s_waitcnt lgkmcnt(0)
	s_barrier
; #define PG8_STAGE(bufoff, gbase, voff) do { _Pragma("unroll") for (int _i = 0; _i < 2; ++_i) \
;         __builtin_amdgcn_global_load_lds((const unsigned*)((const char*)(gbase) + (voff)[_i]), (PG8_LAS unsigned*)(lds + (bufoff) + ldsw + _i * 8192), 16, 0, 0); } while (0)
; #define PG8_LDA(dst, b, h) do { _Pragma("unroll") for (int m = 0; m < 4; ++m) _Pragma("unroll") for (int k = 0; k < 2; ++k) dst[m][k] = *(const PG8_LAS bf16x8*)(lds + PG8_SA(b, h) + aoff + m * 2048 + k * 1024); } while (0)
; #define PG8_LDB(dst, b, h) do { _Pragma("unroll") for (int n = 0; n < 2; ++n) _Pragma("unroll") for (int k = 0; k < 2; ++k) dst[n][k] = *(const PG8_LAS bf16x8*)(lds + PG8_SB(b, h) + boff + n * 2048 + k * 1024); } while (0)
; #define PG8_MMA(ai, bj, At, Bt) do { __builtin_amdgcn_s_setprio(1); _Pragma("unroll") for (int m = 0; m < 4; ++m) _Pragma("unroll") for (int n = 0; n < 2; ++n) _Pragma("unroll") for (int k = 0; k < 2; ++k) \
;         acc[ai][bj][m][n] = __builtin_amdgcn_mfma_f32_16x16x32_bf16(Bt[n][k], At[m][k], acc[ai][bj][m][n], 0, 0, 0); __builtin_amdgcn_s_setprio(0); } while (0)
; #define PG8_WAIT_V(n) asm volatile("s_waitcnt vmcnt(" #n ")" ::: "memory")
; #define PG8_WAIT_L(n) asm volatile("s_waitcnt lgkmcnt(" #n ")" ::: "memory")
; #define PG8_BAR __builtin_amdgcn_s_barrier()
; #define PG8_SCHED __builtin_amdgcn_sched_barrier(0)
; template <class Epi, class Sched, bool ALIGN_EPI = false, bool SP2 = false>
; __device__ __forceinline__ void gemm_phase(PG8_LAS unsigned char* lds, const Gemm g, const Sched& S, const Epi& E) {
;     ...
;             PG8_WAIT_V(8); PG8_WAIT_L(0); PG8_BAR; PG8_MMA(1, 0, At, B0); PG8_MMA(1, 1, At, B1); PG8_BAR; PG8_SCHED;
;             PG8_LDB(B0, 1, 0); PG8_LDB(B1, 1, 1); PG8_SCHED; PG8_LDA(At, 1, 0); PG8_STAGE(PG8_SA(0, 1), a2 + hstep, voffA);
;             PG8_WAIT_V(8); PG8_WAIT_L(0); PG8_BAR; PG8_MMA(0, 0, At, B0); PG8_MMA(0, 1, At, B1); PG8_BAR; PG8_SCHED;
	s_setprio 1
	s_waitcnt lgkmcnt(0)
	v_mfma_f32_16x16x32_bf16 v[54:57], v[144:147], v[180:183], v[54:57]
	v_mfma_f32_16x16x32_bf16 v[54:57], v[148:151], v[184:187], v[54:57]
	v_mfma_f32_16x16x32_bf16 v[50:53], v[152:155], v[180:183], v[50:53]
	v_mfma_f32_16x16x32_bf16 v[50:53], v[156:159], v[184:187], v[50:53]
	v_mfma_f32_16x16x32_bf16 v[62:65], v[160:163], v[180:183], v[62:65]
	v_mfma_f32_16x16x32_bf16 v[62:65], v[164:167], v[184:187], v[62:65]
	v_mfma_f32_16x16x32_bf16 v[58:61], v[168:171], v[180:183], v[58:61]
	v_mfma_f32_16x16x32_bf16 v[58:61], v[172:175], v[184:187], v[58:61]
	v_mfma_f32_16x16x32_bf16 v[38:41], v[144:147], v[188:191], v[38:41]
	v_mfma_f32_16x16x32_bf16 v[38:41], v[148:151], v[192:195], v[38:41]
	v_mfma_f32_16x16x32_bf16 v[34:37], v[152:155], v[188:191], v[34:37]
	v_mfma_f32_16x16x32_bf16 v[34:37], v[156:159], v[192:195], v[34:37]
	v_mfma_f32_16x16x32_bf16 v[46:49], v[160:163], v[188:191], v[46:49]
	v_mfma_f32_16x16x32_bf16 v[46:49], v[164:167], v[192:195], v[46:49]
	v_mfma_f32_16x16x32_bf16 v[42:45], v[168:171], v[188:191], v[42:45]
	v_mfma_f32_16x16x32_bf16 v[42:45], v[172:175], v[192:195], v[42:45]
	v_mfma_f32_16x16x32_bf16 v[22:25], v[144:147], v[202:205], v[22:25]
	v_mfma_f32_16x16x32_bf16 v[22:25], v[148:151], v[206:209], v[22:25]
	v_mfma_f32_16x16x32_bf16 v[18:21], v[152:155], v[202:205], v[18:21]
	v_mfma_f32_16x16x32_bf16 v[18:21], v[156:159], v[206:209], v[18:21]
	v_mfma_f32_16x16x32_bf16 v[30:33], v[160:163], v[202:205], v[30:33]
	v_mfma_f32_16x16x32_bf16 v[30:33], v[164:167], v[206:209], v[30:33]
	v_mfma_f32_16x16x32_bf16 v[26:29], v[168:171], v[202:205], v[26:29]
	v_mfma_f32_16x16x32_bf16 v[26:29], v[172:175], v[206:209], v[26:29]
	v_mfma_f32_16x16x32_bf16 v[6:9], v[144:147], v[210:213], v[6:9]
	v_mfma_f32_16x16x32_bf16 v[6:9], v[148:151], v[214:217], v[6:9]
	v_mfma_f32_16x16x32_bf16 v[2:5], v[152:155], v[210:213], v[2:5]
	v_mfma_f32_16x16x32_bf16 v[2:5], v[156:159], v[214:217], v[2:5]
	v_mfma_f32_16x16x32_bf16 v[10:13], v[160:163], v[210:213], v[10:13]
	v_mfma_f32_16x16x32_bf16 v[10:13], v[164:167], v[214:217], v[10:13]
	v_mfma_f32_16x16x32_bf16 v[14:17], v[168:171], v[210:213], v[14:17]
	v_mfma_f32_16x16x32_bf16 v[14:17], v[172:175], v[214:217], v[14:17]
	s_setprio 0
	s_barrier
	s_add_i32 s18, 0, 0x18000
	v_add_u32_e32 v0, s18, v176
	s_add_i32 vcc_lo, 0, 0x1c000
	ds_read_b128 v[144:147], v0
	ds_read_b128 v[148:151], v0 offset:1024
	ds_read_b128 v[152:155], v0 offset:2048
	ds_read_b128 v[156:159], v0 offset:3072
	v_add_u32_e32 v0, vcc_lo, v176
	ds_read_b128 v[160:163], v0
	ds_read_b128 v[164:167], v0 offset:1024
	ds_read_b128 v[168:171], v0 offset:2048
	ds_read_b128 v[172:175], v0 offset:3072
	s_add_u32 s38, s80, 0x40000
	s_addc_u32 s39, s81, 0
	s_mov_b32 m0, s94
	v_lshl_add_u64 v[226:227], s[38:39], 0, v[136:137]
	ds_read_b128 v[180:183], v178 offset:32768
	ds_read_b128 v[184:187], v178 offset:33792
	ds_read_b128 v[188:191], v178 offset:34816
	ds_read_b128 v[192:195], v178 offset:35840
	ds_read_b128 v[202:205], v178 offset:36864
	ds_read_b128 v[206:209], v178 offset:37888
	ds_read_b128 v[210:213], v178 offset:38912
	ds_read_b128 v[214:217], v178 offset:39936
	global_load_lds_dwordx4 v[226:227], off
	v_lshl_add_u64 v[226:227], s[38:39], 0, v[132:133]
	s_mov_b32 m0, s95
	s_nop 0
	global_load_lds_dwordx4 v[226:227], off
	s_waitcnt vmcnt(8)
	s_waitcnt lgkmcnt(0)
	s_barrier
	s_setprio 1
	s_waitcnt lgkmcnt(0)
	v_mfma_f32_16x16x32_bf16 v[118:121], v[144:147], v[180:183], v[118:121]
	v_mfma_f32_16x16x32_bf16 v[118:121], v[148:151], v[184:187], v[118:121]
	v_mfma_f32_16x16x32_bf16 v[114:117], v[152:155], v[180:183], v[114:117]
	v_mfma_f32_16x16x32_bf16 v[114:117], v[156:159], v[184:187], v[114:117]
	v_mfma_f32_16x16x32_bf16 v[126:129], v[160:163], v[180:183], v[126:129]
	v_mfma_f32_16x16x32_bf16 v[126:129], v[164:167], v[184:187], v[126:129]
	v_mfma_f32_16x16x32_bf16 v[122:125], v[168:171], v[180:183], v[122:125]
	v_mfma_f32_16x16x32_bf16 v[122:125], v[172:175], v[184:187], v[122:125]
	v_mfma_f32_16x16x32_bf16 v[102:105], v[144:147], v[188:191], v[102:105]
	v_mfma_f32_16x16x32_bf16 v[102:105], v[148:151], v[192:195], v[102:105]
	v_mfma_f32_16x16x32_bf16 v[98:101], v[152:155], v[188:191], v[98:101]
	v_mfma_f32_16x16x32_bf16 v[98:101], v[156:159], v[192:195], v[98:101]
	v_mfma_f32_16x16x32_bf16 v[110:113], v[160:163], v[188:191], v[110:113]
	v_mfma_f32_16x16x32_bf16 v[110:113], v[164:167], v[192:195], v[110:113]
	v_mfma_f32_16x16x32_bf16 v[106:109], v[168:171], v[188:191], v[106:109]
	v_mfma_f32_16x16x32_bf16 v[106:109], v[172:175], v[192:195], v[106:109]
	v_mfma_f32_16x16x32_bf16 v[86:89], v[144:147], v[202:205], v[86:89]
	v_mfma_f32_16x16x32_bf16 v[86:89], v[148:151], v[206:209], v[86:89]
	v_mfma_f32_16x16x32_bf16 v[82:85], v[152:155], v[202:205], v[82:85]
	v_mfma_f32_16x16x32_bf16 v[82:85], v[156:159], v[206:209], v[82:85]
	v_mfma_f32_16x16x32_bf16 v[94:97], v[160:163], v[202:205], v[94:97]
	v_mfma_f32_16x16x32_bf16 v[94:97], v[164:167], v[206:209], v[94:97]
	v_mfma_f32_16x16x32_bf16 v[90:93], v[168:171], v[202:205], v[90:93]
	v_mfma_f32_16x16x32_bf16 v[90:93], v[172:175], v[206:209], v[90:93]
	v_mfma_f32_16x16x32_bf16 v[70:73], v[144:147], v[210:213], v[70:73]
	v_mfma_f32_16x16x32_bf16 v[70:73], v[148:151], v[214:217], v[70:73]
	v_mfma_f32_16x16x32_bf16 v[66:69], v[152:155], v[210:213], v[66:69]
	v_mfma_f32_16x16x32_bf16 v[66:69], v[156:159], v[214:217], v[66:69]
	v_mfma_f32_16x16x32_bf16 v[78:81], v[160:163], v[210:213], v[78:81]
	v_mfma_f32_16x16x32_bf16 v[78:81], v[164:167], v[214:217], v[78:81]
	v_mfma_f32_16x16x32_bf16 v[74:77], v[168:171], v[210:213], v[74:77]
	v_mfma_f32_16x16x32_bf16 v[74:77], v[172:175], v[214:217], v[74:77]
	s_setprio 0
	s_barrier
; #define PG8_STAGE(bufoff, gbase, voff) do { _Pragma("unroll") for (int _i = 0; _i < 2; ++_i) \
;         __builtin_amdgcn_global_load_lds((const unsigned*)((const char*)(gbase) + (voff)[_i]), (PG8_LAS unsigned*)(lds + (bufoff) + ldsw + _i * 8192), 16, 0, 0); } while (0)
; #define PG8_LDA(dst, b, h) do { _Pragma("unroll") for (int m = 0; m < 4; ++m) _Pragma("unroll") for (int k = 0; k < 2; ++k) dst[m][k] = *(const PG8_LAS bf16x8*)(lds + PG8_SA(b, h) + aoff + m * 2048 + k * 1024); } while (0)
; #define PG8_LDB(dst, b, h) do { _Pragma("unroll") for (int n = 0; n < 2; ++n) _Pragma("unroll") for (int k = 0; k < 2; ++k) dst[n][k] = *(const PG8_LAS bf16x8*)(lds + PG8_SB(b, h) + boff + n * 2048 + k * 1024); } while (0)
; template <class Epi, class Sched, bool ALIGN_EPI = false, bool SP2 = false>
; __device__ __forceinline__ void gemm_phase(PG8_LAS unsigned char* lds, const Gemm g, const Sched& S, const Epi& E) {
;     ...
;         for (int t = 0; t < nt; t += 2) {
;             const bool last = (t == nt - 2);
;             const char* a1 = cA + (size_t)(t + 1) * kstep;
;             const char* a2 = last ? nA : cA + (size_t)(t + 2) * kstep; const char* b2 = last ? nB : cB + (size_t)(t + 2) * kstep;
;             const char* a3 = a2 + kstep; const char* b3 = b2 + kstep;
;             if (last && has_next) S.a_ready(nxt);
;             if constexpr (SP2) {
;             PG8_LDB(B0, 0, 0); PG8_LDB(B1, 0, 1); PG8_SCHED; PG8_LDA(At, 0, 0); PG8_STAGE(PG8_SA(1, 1), a1 + hstep, voffA);
;             PG8_WAIT_V(8); PG8_WAIT_L(0); PG8_BAR; PG8_MMA(0, 0, At, B0); PG8_MMA(0, 1, At, B1); PG8_BAR; PG8_SCHED;
;             PG8_LDA(At, 0, 1); PG8_STAGE(PG8_SB(0, 0), b2, voffB); PG8_STAGE(PG8_SB(0, 1), b2 + hstep, voffB); PG8_STAGE(PG8_SA(0, 0), a2, voffA);
;             PG8_WAIT_V(8); PG8_WAIT_L(0); PG8_BAR; PG8_MMA(1, 0, At, B0); PG8_MMA(1, 1, At, B1); PG8_BAR; PG8_SCHED;
;             PG8_LDB(B0, 1, 0); PG8_LDB(B1, 1, 1); PG8_SCHED; PG8_LDA(At, 1, 0); PG8_STAGE(PG8_SA(0, 1), a2 + hstep, voffA);
;             PG8_WAIT_V(8); PG8_WAIT_L(0); PG8_BAR; PG8_MMA(0, 0, At, B0); PG8_MMA(0, 1, At, B1); PG8_BAR; PG8_SCHED;
;             PG8_LDA(At, 1, 1); PG8_STAGE(PG8_SB(1, 0), b3, voffB); PG8_STAGE(PG8_SB(1, 1), b3 + hstep, voffB); PG8_STAGE(PG8_SA(1, 0), a3, voffA);
;             PG8_WAIT_V(8); PG8_WAIT_L(0); PG8_BAR; PG8_MMA(1, 0, At, B0); PG8_MMA(1, 1, At, B1); PG8_BAR; PG8_SCHED;
	s_add_i32 s18, s18, s91
	v_lshl_add_u64 v[218:219], v[218:219], 0, s[30:31]
	s_mov_b32 m0, s18
	ds_read_b128 v[180:183], v178 offset:49152
	ds_read_b128 v[184:187], v178 offset:50176
	ds_read_b128 v[188:191], v178 offset:51200
	ds_read_b128 v[192:195], v178 offset:52224
	ds_read_b128 v[202:205], v178 offset:53248
	ds_read_b128 v[206:209], v178 offset:54272
	ds_read_b128 v[210:213], v178 offset:55296
	ds_read_b128 v[214:217], v178 offset:56320
	global_load_lds_dwordx4 v[218:219], off
	s_add_i32 m0, s18, 0x2000
	s_add_u32 s38, s44, 0x40080
	v_lshl_add_u64 v[218:219], v[220:221], 0, s[30:31]
	s_addc_u32 s39, s45, 0
	s_add_i32 s18, vcc_lo, s91
	global_load_lds_dwordx4 v[218:219], off
	v_lshl_add_u64 v[218:219], s[38:39], 0, v[134:135]
	s_mov_b32 m0, s18
	s_nop 0
	global_load_lds_dwordx4 v[218:219], off
	v_lshl_add_u64 v[218:219], s[38:39], 0, v[130:131]
	s_add_i32 m0, s18, 0x2000
	s_nop 0
	global_load_lds_dwordx4 v[218:219], off
	v_lshl_add_u64 v[218:219], v[222:223], 0, s[30:31]
	s_mov_b32 m0, s7
	s_nop 0
	global_load_lds_dwordx4 v[218:219], off
	v_lshl_add_u64 v[218:219], v[224:225], 0, s[30:31]
	s_mov_b32 m0, s96
	s_nop 0
	global_load_lds_dwordx4 v[218:219], off
	s_waitcnt vmcnt(8)
	s_waitcnt lgkmcnt(0)
	s_barrier
	s_setprio 1
	s_waitcnt lgkmcnt(0)
	v_mfma_f32_16x16x32_bf16 v[54:57], v[144:147], v[180:183], v[54:57]
	v_mfma_f32_16x16x32_bf16 v[54:57], v[148:151], v[184:187], v[54:57]
	v_mfma_f32_16x16x32_bf16 v[50:53], v[152:155], v[180:183], v[50:53]
	v_mfma_f32_16x16x32_bf16 v[50:53], v[156:159], v[184:187], v[50:53]
	v_mfma_f32_16x16x32_bf16 v[62:65], v[160:163], v[180:183], v[62:65]
	v_mfma_f32_16x16x32_bf16 v[62:65], v[164:167], v[184:187], v[62:65]
	v_mfma_f32_16x16x32_bf16 v[58:61], v[168:171], v[180:183], v[58:61]
	v_mfma_f32_16x16x32_bf16 v[58:61], v[172:175], v[184:187], v[58:61]
	v_mfma_f32_16x16x32_bf16 v[38:41], v[144:147], v[188:191], v[38:41]
	v_mfma_f32_16x16x32_bf16 v[38:41], v[148:151], v[192:195], v[38:41]
	v_mfma_f32_16x16x32_bf16 v[34:37], v[152:155], v[188:191], v[34:37]
	v_mfma_f32_16x16x32_bf16 v[34:37], v[156:159], v[192:195], v[34:37]
	v_mfma_f32_16x16x32_bf16 v[46:49], v[160:163], v[188:191], v[46:49]
	v_mfma_f32_16x16x32_bf16 v[46:49], v[164:167], v[192:195], v[46:49]
	v_mfma_f32_16x16x32_bf16 v[42:45], v[168:171], v[188:191], v[42:45]
	v_mfma_f32_16x16x32_bf16 v[42:45], v[172:175], v[192:195], v[42:45]
	v_mfma_f32_16x16x32_bf16 v[22:25], v[144:147], v[202:205], v[22:25]
	v_mfma_f32_16x16x32_bf16 v[22:25], v[148:151], v[206:209], v[22:25]
	v_mfma_f32_16x16x32_bf16 v[18:21], v[152:155], v[202:205], v[18:21]
	v_mfma_f32_16x16x32_bf16 v[18:21], v[156:159], v[206:209], v[18:21]
	v_mfma_f32_16x16x32_bf16 v[30:33], v[160:163], v[202:205], v[30:33]
	v_mfma_f32_16x16x32_bf16 v[30:33], v[164:167], v[206:209], v[30:33]
	v_mfma_f32_16x16x32_bf16 v[26:29], v[168:171], v[202:205], v[26:29]
	v_mfma_f32_16x16x32_bf16 v[26:29], v[172:175], v[206:209], v[26:29]
	v_mfma_f32_16x16x32_bf16 v[6:9], v[144:147], v[210:213], v[6:9]
	v_mfma_f32_16x16x32_bf16 v[6:9], v[148:151], v[214:217], v[6:9]
	v_mfma_f32_16x16x32_bf16 v[2:5], v[152:155], v[210:213], v[2:5]
	v_mfma_f32_16x16x32_bf16 v[2:5], v[156:159], v[214:217], v[2:5]
	v_mfma_f32_16x16x32_bf16 v[10:13], v[160:163], v[210:213], v[10:13]
	v_mfma_f32_16x16x32_bf16 v[10:13], v[164:167], v[214:217], v[10:13]
	v_mfma_f32_16x16x32_bf16 v[14:17], v[168:171], v[210:213], v[14:17]
	v_mfma_f32_16x16x32_bf16 v[14:17], v[172:175], v[214:217], v[14:17]
	s_setprio 0
	s_barrier
	s_add_i32 s85, s85, 2
	s_add_u32 s46, s46, 0x100
	s_addc_u32 s47, s47, 0
	s_add_u32 s83, s83, 0x100
	s_addc_u32 s84, s84, 0
	s_cmp_gt_u32 s85, 13
	s_cbranch_scc0 .LBB0_132
	s_and_b64 vcc, exec, s[10:11]
	s_cbranch_vccz .LBB0_135
	s_barrier

; #define PG8_STAGE(bufoff, gbase, voff) do { _Pragma("unroll") for (int _i = 0; _i < 2; ++_i) \
;         __builtin_amdgcn_global_load_lds((const unsigned*)((const char*)(gbase) + (voff)[_i]), (PG8_LAS unsigned*)(lds + (bufoff) + ldsw + _i * 8192), 16, 0, 0); } while (0)
; #define PG8_LDA(dst, b, h) do { _Pragma("unroll") for (int m = 0; m < 4; ++m) _Pragma("unroll") for (int k = 0; k < 2; ++k) dst[m][k] = *(const PG8_LAS bf16x8*)(lds + PG8_SA(b, h) + aoff + m * 2048 + k * 1024); } while (0)
; #define PG8_LDB(dst, b, h) do { _Pragma("unroll") for (int n = 0; n < 2; ++n) _Pragma("unroll") for (int k = 0; k < 2; ++k) dst[n][k] = *(const PG8_LAS bf16x8*)(lds + PG8_SB(b, h) + boff + n * 2048 + k * 1024); } while (0)
; #define PG8_MMA(ai, bj, At, Bt) do { __builtin_amdgcn_s_setprio(1); _Pragma("unroll") for (int m = 0; m < 4; ++m) _Pragma("unroll") for (int n = 0; n < 2; ++n) _Pragma("unroll") for (int k = 0; k < 2; ++k) \
;         acc[ai][bj][m][n] = __builtin_amdgcn_mfma_f32_16x16x32_bf16(Bt[n][k], At[m][k], acc[ai][bj][m][n], 0, 0, 0); __builtin_amdgcn_s_setprio(0); } while (0)
; #define PG8_WAIT_V(n) asm volatile("s_waitcnt vmcnt(" #n ")" ::: "memory")
; #define PG8_WAIT_L(n) asm volatile("s_waitcnt lgkmcnt(" #n ")" ::: "memory")
; #define PG8_BAR __builtin_amdgcn_s_barrier()
; #define PG8_SCHED __builtin_amdgcn_sched_barrier(0)
; template <class Epi, class Sched, bool ALIGN_EPI = false, bool SP2 = false>
; __device__ __forceinline__ void gemm_phase(PG8_LAS unsigned char* lds, const Gemm g, const Sched& S, const Epi& E) {
;     ...
;         for (int t = 0; t < nt; t += 2) {
;             const bool last = (t == nt - 2);
;             const char* a1 = cA + (size_t)(t + 1) * kstep;
;             const char* a2 = last ? nA : cA + (size_t)(t + 2) * kstep; const char* b2 = last ? nB : cB + (size_t)(t + 2) * kstep;
;             const char* a3 = a2 + kstep; const char* b3 = b2 + kstep;
;             if (last && has_next) S.a_ready(nxt);
;             if constexpr (SP2) {
;             PG8_LDB(B0, 0, 0); PG8_LDB(B1, 0, 1); PG8_SCHED; PG8_LDA(At, 0, 0); PG8_STAGE(PG8_SA(1, 1), a1 + hstep, voffA);
;             PG8_WAIT_V(8); PG8_WAIT_L(0); PG8_BAR; PG8_MMA(0, 0, At, B0); PG8_MMA(0, 1, At, B1); PG8_BAR; PG8_SCHED;
;             PG8_LDA(At, 0, 1); PG8_STAGE(PG8_SB(0, 0), b2, voffB); PG8_STAGE(PG8_SB(0, 1), b2 + hstep, voffB); PG8_STAGE(PG8_SA(0, 0), a2, voffA);
.LBB0_220:
	s_add_u32 s18, s60, 0xfffc0080
	s_addc_u32 s38, s61, -1
	s_add_i32 s39, 0, 0x10000
	s_cmp_eq_u32 s82, 12
	s_cselect_b32 s65, s47, s38
	s_cselect_b32 s64, s78, s18
	v_add_u32_e32 v145, s39, v141
	s_cselect_b32 s57, s49, s81
	s_cselect_b32 s56, s79, s80
	s_add_i32 s18, 0, 0x14000
	ds_read_b128 v[146:149], v145
	ds_read_b128 v[150:153], v145 offset:1024
	ds_read_b128 v[154:157], v145 offset:2048
	ds_read_b128 v[158:161], v145 offset:3072
	v_add_u32_e32 v145, s18, v141
	ds_read_b128 v[162:165], v145
	ds_read_b128 v[166:169], v145 offset:1024
	ds_read_b128 v[170:173], v145 offset:2048
	ds_read_b128 v[174:177], v145 offset:3072
	v_lshl_add_u64 v[194:195], s[60:61], 0, v[136:137]
	s_add_i32 m0, s29, 0xc000
	ds_read_b128 v[178:181], v144
	ds_read_b128 v[182:185], v144 offset:1024
	ds_read_b128 v[186:189], v144 offset:2048
	ds_read_b128 v[190:193], v144 offset:3072
	ds_read_b128 v[202:205], v144 offset:4096
	ds_read_b128 v[206:209], v144 offset:5120
	ds_read_b128 v[210:213], v144 offset:6144
	ds_read_b128 v[214:217], v144 offset:7168
	global_load_lds_dwordx4 v[194:195], off
	v_lshl_add_u64 v[194:195], s[60:61], 0, v[138:139]
	s_add_i32 m0, s29, 0xe000
	s_nop 0
	global_load_lds_dwordx4 v[194:195], off
	s_waitcnt vmcnt(8)
	s_waitcnt lgkmcnt(0)
	s_barrier
	s_setprio 1
	s_waitcnt lgkmcnt(0)
	v_mfma_f32_16x16x32_bf16 v[114:117], v[146:149], v[178:181], v[114:117]
	v_mfma_f32_16x16x32_bf16 v[114:117], v[150:153], v[182:185], v[114:117]
	v_mfma_f32_16x16x32_bf16 v[118:121], v[154:157], v[178:181], v[118:121]
	v_mfma_f32_16x16x32_bf16 v[118:121], v[158:161], v[182:185], v[118:121]
	v_mfma_f32_16x16x32_bf16 v[122:125], v[162:165], v[178:181], v[122:125]
	v_mfma_f32_16x16x32_bf16 v[122:125], v[166:169], v[182:185], v[122:125]
	v_mfma_f32_16x16x32_bf16 v[126:129], v[170:173], v[178:181], v[126:129]
	v_mfma_f32_16x16x32_bf16 v[126:129], v[174:177], v[182:185], v[126:129]
	v_mfma_f32_16x16x32_bf16 v[98:101], v[146:149], v[186:189], v[98:101]
	v_mfma_f32_16x16x32_bf16 v[98:101], v[150:153], v[190:193], v[98:101]
	v_mfma_f32_16x16x32_bf16 v[102:105], v[154:157], v[186:189], v[102:105]
	v_mfma_f32_16x16x32_bf16 v[102:105], v[158:161], v[190:193], v[102:105]
	v_mfma_f32_16x16x32_bf16 v[106:109], v[162:165], v[186:189], v[106:109]
	v_mfma_f32_16x16x32_bf16 v[106:109], v[166:169], v[190:193], v[106:109]
	v_mfma_f32_16x16x32_bf16 v[110:113], v[170:173], v[186:189], v[110:113]
	v_mfma_f32_16x16x32_bf16 v[110:113], v[174:177], v[190:193], v[110:113]
	v_mfma_f32_16x16x32_bf16 v[82:85], v[146:149], v[202:205], v[82:85]
	v_mfma_f32_16x16x32_bf16 v[82:85], v[150:153], v[206:209], v[82:85]
	v_mfma_f32_16x16x32_bf16 v[86:89], v[154:157], v[202:205], v[86:89]
	v_mfma_f32_16x16x32_bf16 v[86:89], v[158:161], v[206:209], v[86:89]
	v_mfma_f32_16x16x32_bf16 v[90:93], v[162:165], v[202:205], v[90:93]
	v_mfma_f32_16x16x32_bf16 v[90:93], v[166:169], v[206:209], v[90:93]
	v_mfma_f32_16x16x32_bf16 v[94:97], v[170:173], v[202:205], v[94:97]
	v_mfma_f32_16x16x32_bf16 v[94:97], v[174:177], v[206:209], v[94:97]
	v_mfma_f32_16x16x32_bf16 v[66:69], v[146:149], v[210:213], v[66:69]
	v_mfma_f32_16x16x32_bf16 v[66:69], v[150:153], v[214:217], v[66:69]
	v_mfma_f32_16x16x32_bf16 v[70:73], v[154:157], v[210:213], v[70:73]
	v_mfma_f32_16x16x32_bf16 v[70:73], v[158:161], v[214:217], v[70:73]
	v_mfma_f32_16x16x32_bf16 v[74:77], v[162:165], v[210:213], v[74:77]
	v_mfma_f32_16x16x32_bf16 v[74:77], v[166:169], v[214:217], v[74:77]
	v_mfma_f32_16x16x32_bf16 v[78:81], v[170:173], v[210:213], v[78:81]
	v_mfma_f32_16x16x32_bf16 v[78:81], v[174:177], v[214:217], v[78:81]
	s_setprio 0
	s_barrier
	s_add_i32 s38, s39, s27
	v_lshl_add_u64 v[194:195], s[56:57], 0, v[0:1]
	s_mov_b32 m0, s38
	ds_read_b128 v[178:181], v144 offset:16384
	ds_read_b128 v[182:185], v144 offset:17408
	ds_read_b128 v[186:189], v144 offset:18432
	ds_read_b128 v[190:193], v144 offset:19456
	ds_read_b128 v[202:205], v144 offset:20480
	ds_read_b128 v[206:209], v144 offset:21504
	ds_read_b128 v[210:213], v144 offset:22528
	ds_read_b128 v[214:217], v144 offset:23552
	global_load_lds_dwordx4 v[194:195], off
	s_add_i32 m0, s38, 0x2000
	s_add_u32 s38, s56, 0x40000
	v_lshl_add_u64 v[218:219], s[56:57], 0, v[130:131]
	s_addc_u32 s39, s57, 0
	s_add_i32 s18, s18, s27
	global_load_lds_dwordx4 v[218:219], off
	v_lshl_add_u64 v[220:221], s[38:39], 0, v[0:1]
	s_mov_b32 m0, s18
	v_lshl_add_u64 v[222:223], s[64:65], 0, v[132:133]
	global_load_lds_dwordx4 v[220:221], off
	v_lshl_add_u64 v[220:221], s[38:39], 0, v[130:131]
	s_add_i32 m0, s18, 0x2000
	s_nop 0
	global_load_lds_dwordx4 v[220:221], off
	v_lshl_add_u64 v[220:221], s[64:65], 0, v[134:135]
	s_mov_b32 m0, s29
	s_nop 0
	global_load_lds_dwordx4 v[220:221], off
	s_mov_b32 m0, s33
	s_nop 0
	global_load_lds_dwordx4 v[222:223], off
	s_waitcnt vmcnt(8)
	s_waitcnt lgkmcnt(0)
	s_barrier
; #define PG8_STAGE(bufoff, gbase, voff) do { _Pragma("unroll") for (int _i = 0; _i < 2; ++_i) \
;         __builtin_amdgcn_global_load_lds((const unsigned*)((const char*)(gbase) + (voff)[_i]), (PG8_LAS unsigned*)(lds + (bufoff) + ldsw + _i * 8192), 16, 0, 0); } while (0)
; #define PG8_LDA(dst, b, h) do { _Pragma("unroll") for (int m = 0; m < 4; ++m) _Pragma("unroll") for (int k = 0; k < 2; ++k) dst[m][k] = *(const PG8_LAS bf16x8*)(lds + PG8_SA(b, h) + aoff + m * 2048 + k * 1024); } while (0)
; #define PG8_LDB(dst, b, h) do { _Pragma("unroll") for (int n = 0; n < 2; ++n) _Pragma("unroll") for (int k = 0; k < 2; ++k) dst[n][k] = *(const PG8_LAS bf16x8*)(lds + PG8_SB(b, h) + boff + n * 2048 + k * 1024); } while (0)
; #define PG8_MMA(ai, bj, At, Bt) do { __builtin_amdgcn_s_setprio(1); _Pragma("unroll") for (int m = 0; m < 4; ++m) _Pragma("unroll") for (int n = 0; n < 2; ++n) _Pragma("unroll") for (int k = 0; k < 2; ++k) \
;         acc[ai][bj][m][n] = __builtin_amdgcn_mfma_f32_16x16x32_bf16(Bt[n][k], At[m][k], acc[ai][bj][m][n], 0, 0, 0); __builtin_amdgcn_s_setprio(0); } while (0)
; #define PG8_WAIT_V(n) asm volatile("s_waitcnt vmcnt(" #n ")" ::: "memory")
; #define PG8_WAIT_L(n) asm volatile("s_waitcnt lgkmcnt(" #n ")" ::: "memory")
; #define PG8_BAR __builtin_amdgcn_s_barrier()
; #define PG8_SCHED __builtin_amdgcn_sched_barrier(0)
; template <class Epi, class Sched, bool ALIGN_EPI = false, bool SP2 = false>
; __device__ __forceinline__ void gemm_phase(PG8_LAS unsigned char* lds, const Gemm g, const Sched& S, const Epi& E) {
;     ...
;             PG8_WAIT_V(8); PG8_WAIT_L(0); PG8_BAR; PG8_MMA(1, 0, At, B0); PG8_MMA(1, 1, At, B1); PG8_BAR; PG8_SCHED;
;             PG8_LDB(B0, 1, 0); PG8_LDB(B1, 1, 1); PG8_SCHED; PG8_LDA(At, 1, 0); PG8_STAGE(PG8_SA(0, 1), a2 + hstep, voffA);
;             PG8_WAIT_V(8); PG8_WAIT_L(0); PG8_BAR; PG8_MMA(0, 0, At, B0); PG8_MMA(0, 1, At, B1); PG8_BAR; PG8_SCHED;
	s_setprio 1
	s_waitcnt lgkmcnt(0)
	v_mfma_f32_16x16x32_bf16 v[50:53], v[146:149], v[178:181], v[50:53]
	v_mfma_f32_16x16x32_bf16 v[50:53], v[150:153], v[182:185], v[50:53]
	v_mfma_f32_16x16x32_bf16 v[54:57], v[154:157], v[178:181], v[54:57]
	v_mfma_f32_16x16x32_bf16 v[54:57], v[158:161], v[182:185], v[54:57]
	v_mfma_f32_16x16x32_bf16 v[58:61], v[162:165], v[178:181], v[58:61]
	v_mfma_f32_16x16x32_bf16 v[58:61], v[166:169], v[182:185], v[58:61]
	v_mfma_f32_16x16x32_bf16 v[62:65], v[170:173], v[178:181], v[62:65]
	v_mfma_f32_16x16x32_bf16 v[62:65], v[174:177], v[182:185], v[62:65]
	v_mfma_f32_16x16x32_bf16 v[34:37], v[146:149], v[186:189], v[34:37]
	v_mfma_f32_16x16x32_bf16 v[34:37], v[150:153], v[190:193], v[34:37]
	v_mfma_f32_16x16x32_bf16 v[38:41], v[154:157], v[186:189], v[38:41]
	v_mfma_f32_16x16x32_bf16 v[38:41], v[158:161], v[190:193], v[38:41]
	v_mfma_f32_16x16x32_bf16 v[42:45], v[162:165], v[186:189], v[42:45]
	v_mfma_f32_16x16x32_bf16 v[42:45], v[166:169], v[190:193], v[42:45]
	v_mfma_f32_16x16x32_bf16 v[46:49], v[170:173], v[186:189], v[46:49]
	v_mfma_f32_16x16x32_bf16 v[46:49], v[174:177], v[190:193], v[46:49]
	v_mfma_f32_16x16x32_bf16 v[18:21], v[146:149], v[202:205], v[18:21]
	v_mfma_f32_16x16x32_bf16 v[18:21], v[150:153], v[206:209], v[18:21]
	v_mfma_f32_16x16x32_bf16 v[22:25], v[154:157], v[202:205], v[22:25]
	v_mfma_f32_16x16x32_bf16 v[22:25], v[158:161], v[206:209], v[22:25]
	v_mfma_f32_16x16x32_bf16 v[26:29], v[162:165], v[202:205], v[26:29]
	v_mfma_f32_16x16x32_bf16 v[26:29], v[166:169], v[206:209], v[26:29]
	v_mfma_f32_16x16x32_bf16 v[30:33], v[170:173], v[202:205], v[30:33]
	v_mfma_f32_16x16x32_bf16 v[30:33], v[174:177], v[206:209], v[30:33]
	v_mfma_f32_16x16x32_bf16 v[2:5], v[146:149], v[210:213], v[2:5]
	v_mfma_f32_16x16x32_bf16 v[2:5], v[150:153], v[214:217], v[2:5]
	v_mfma_f32_16x16x32_bf16 v[6:9], v[154:157], v[210:213], v[6:9]
	v_mfma_f32_16x16x32_bf16 v[6:9], v[158:161], v[214:217], v[6:9]
	v_mfma_f32_16x16x32_bf16 v[10:13], v[162:165], v[210:213], v[10:13]
	v_mfma_f32_16x16x32_bf16 v[10:13], v[166:169], v[214:217], v[10:13]
	v_mfma_f32_16x16x32_bf16 v[14:17], v[170:173], v[210:213], v[14:17]
	v_mfma_f32_16x16x32_bf16 v[14:17], v[174:177], v[214:217], v[14:17]
	s_setprio 0
	s_barrier
	s_add_i32 s18, 0, 0x18000
	v_add_u32_e32 v145, s18, v141
	s_add_i32 s83, 0, 0x1c000
	ds_read_b128 v[146:149], v145
	ds_read_b128 v[150:153], v145 offset:1024
	ds_read_b128 v[154:157], v145 offset:2048
	ds_read_b128 v[158:161], v145 offset:3072
	v_add_u32_e32 v145, s83, v141
	ds_read_b128 v[162:165], v145
	ds_read_b128 v[166:169], v145 offset:1024
	ds_read_b128 v[170:173], v145 offset:2048
	ds_read_b128 v[174:177], v145 offset:3072
	s_add_u32 s38, s64, 0x40000
	s_addc_u32 s39, s65, 0
	s_mov_b32 m0, s58
	v_lshl_add_u64 v[224:225], s[38:39], 0, v[134:135]
	ds_read_b128 v[178:181], v144 offset:32768
	ds_read_b128 v[182:185], v144 offset:33792
	ds_read_b128 v[186:189], v144 offset:34816
	ds_read_b128 v[190:193], v144 offset:35840
	ds_read_b128 v[202:205], v144 offset:36864
	ds_read_b128 v[206:209], v144 offset:37888
	ds_read_b128 v[210:213], v144 offset:38912
	ds_read_b128 v[214:217], v144 offset:39936
	global_load_lds_dwordx4 v[224:225], off
	v_lshl_add_u64 v[224:225], s[38:39], 0, v[132:133]
	s_mov_b32 m0, s69
	s_nop 0
	global_load_lds_dwordx4 v[224:225], off
	s_waitcnt vmcnt(8)
	s_waitcnt lgkmcnt(0)
	s_barrier
	s_setprio 1
	s_waitcnt lgkmcnt(0)
	v_mfma_f32_16x16x32_bf16 v[114:117], v[146:149], v[178:181], v[114:117]
	v_mfma_f32_16x16x32_bf16 v[114:117], v[150:153], v[182:185], v[114:117]
	v_mfma_f32_16x16x32_bf16 v[118:121], v[154:157], v[178:181], v[118:121]
	v_mfma_f32_16x16x32_bf16 v[118:121], v[158:161], v[182:185], v[118:121]
	v_mfma_f32_16x16x32_bf16 v[122:125], v[162:165], v[178:181], v[122:125]
	v_mfma_f32_16x16x32_bf16 v[122:125], v[166:169], v[182:185], v[122:125]
	v_mfma_f32_16x16x32_bf16 v[126:129], v[170:173], v[178:181], v[126:129]
	v_mfma_f32_16x16x32_bf16 v[126:129], v[174:177], v[182:185], v[126:129]
	v_mfma_f32_16x16x32_bf16 v[98:101], v[146:149], v[186:189], v[98:101]
	v_mfma_f32_16x16x32_bf16 v[98:101], v[150:153], v[190:193], v[98:101]
	v_mfma_f32_16x16x32_bf16 v[102:105], v[154:157], v[186:189], v[102:105]
	v_mfma_f32_16x16x32_bf16 v[102:105], v[158:161], v[190:193], v[102:105]
	v_mfma_f32_16x16x32_bf16 v[106:109], v[162:165], v[186:189], v[106:109]
	v_mfma_f32_16x16x32_bf16 v[106:109], v[166:169], v[190:193], v[106:109]
	v_mfma_f32_16x16x32_bf16 v[110:113], v[170:173], v[186:189], v[110:113]
	v_mfma_f32_16x16x32_bf16 v[110:113], v[174:177], v[190:193], v[110:113]
	v_mfma_f32_16x16x32_bf16 v[82:85], v[146:149], v[202:205], v[82:85]
	v_mfma_f32_16x16x32_bf16 v[82:85], v[150:153], v[206:209], v[82:85]
	v_mfma_f32_16x16x32_bf16 v[86:89], v[154:157], v[202:205], v[86:89]
	v_mfma_f32_16x16x32_bf16 v[86:89], v[158:161], v[206:209], v[86:89]
	v_mfma_f32_16x16x32_bf16 v[90:93], v[162:165], v[202:205], v[90:93]
	v_mfma_f32_16x16x32_bf16 v[90:93], v[166:169], v[206:209], v[90:93]
	v_mfma_f32_16x16x32_bf16 v[94:97], v[170:173], v[202:205], v[94:97]
	v_mfma_f32_16x16x32_bf16 v[94:97], v[174:177], v[206:209], v[94:97]
	v_mfma_f32_16x16x32_bf16 v[66:69], v[146:149], v[210:213], v[66:69]
	v_mfma_f32_16x16x32_bf16 v[66:69], v[150:153], v[214:217], v[66:69]
	v_mfma_f32_16x16x32_bf16 v[70:73], v[154:157], v[210:213], v[70:73]
	v_mfma_f32_16x16x32_bf16 v[70:73], v[158:161], v[214:217], v[70:73]
	v_mfma_f32_16x16x32_bf16 v[74:77], v[162:165], v[210:213], v[74:77]
	v_mfma_f32_16x16x32_bf16 v[74:77], v[166:169], v[214:217], v[74:77]
	v_mfma_f32_16x16x32_bf16 v[78:81], v[170:173], v[210:213], v[78:81]
	v_mfma_f32_16x16x32_bf16 v[78:81], v[174:177], v[214:217], v[78:81]
	s_setprio 0
	s_barrier
; #define PG8_STAGE(bufoff, gbase, voff) do { _Pragma("unroll") for (int _i = 0; _i < 2; ++_i) \
;         __builtin_amdgcn_global_load_lds((const unsigned*)((const char*)(gbase) + (voff)[_i]), (PG8_LAS unsigned*)(lds + (bufoff) + ldsw + _i * 8192), 16, 0, 0); } while (0)
; #define PG8_LDA(dst, b, h) do { _Pragma("unroll") for (int m = 0; m < 4; ++m) _Pragma("unroll") for (int k = 0; k < 2; ++k) dst[m][k] = *(const PG8_LAS bf16x8*)(lds + PG8_SA(b, h) + aoff + m * 2048 + k * 1024); } while (0)
; #define PG8_LDB(dst, b, h) do { _Pragma("unroll") for (int n = 0; n < 2; ++n) _Pragma("unroll") for (int k = 0; k < 2; ++k) dst[n][k] = *(const PG8_LAS bf16x8*)(lds + PG8_SB(b, h) + boff + n * 2048 + k * 1024); } while (0)
; template <class Epi, class Sched, bool ALIGN_EPI = false, bool SP2 = false>
; __device__ __forceinline__ void gemm_phase(PG8_LAS unsigned char* lds, const Gemm g, const Sched& S, const Epi& E) {
;     ...
;         for (int t = 0; t < nt; t += 2) {
;             const bool last = (t == nt - 2);
;             const char* a1 = cA + (size_t)(t + 1) * kstep;
;             const char* a2 = last ? nA : cA + (size_t)(t + 2) * kstep; const char* b2 = last ? nB : cB + (size_t)(t + 2) * kstep;
;             const char* a3 = a2 + kstep; const char* b3 = b2 + kstep;
;             if (last && has_next) S.a_ready(nxt);
;             if constexpr (SP2) {
;             PG8_LDB(B0, 0, 0); PG8_LDB(B1, 0, 1); PG8_SCHED; PG8_LDA(At, 0, 0); PG8_STAGE(PG8_SA(1, 1), a1 + hstep, voffA);
;             PG8_WAIT_V(8); PG8_WAIT_L(0); PG8_BAR; PG8_MMA(0, 0, At, B0); PG8_MMA(0, 1, At, B1); PG8_BAR; PG8_SCHED;
;             PG8_LDA(At, 0, 1); PG8_STAGE(PG8_SB(0, 0), b2, voffB); PG8_STAGE(PG8_SB(0, 1), b2 + hstep, voffB); PG8_STAGE(PG8_SA(0, 0), a2, voffA);
;             PG8_WAIT_V(8); PG8_WAIT_L(0); PG8_BAR; PG8_MMA(1, 0, At, B0); PG8_MMA(1, 1, At, B1); PG8_BAR; PG8_SCHED;
;             PG8_LDB(B0, 1, 0); PG8_LDB(B1, 1, 1); PG8_SCHED; PG8_LDA(At, 1, 0); PG8_STAGE(PG8_SA(0, 1), a2 + hstep, voffA);
;             PG8_WAIT_V(8); PG8_WAIT_L(0); PG8_BAR; PG8_MMA(0, 0, At, B0); PG8_MMA(0, 1, At, B1); PG8_BAR; PG8_SCHED;
;             PG8_LDA(At, 1, 1); PG8_STAGE(PG8_SB(1, 0), b3, voffB); PG8_STAGE(PG8_SB(1, 1), b3 + hstep, voffB); PG8_STAGE(PG8_SA(1, 0), a3, voffA);
;             PG8_WAIT_V(8); PG8_WAIT_L(0); PG8_BAR; PG8_MMA(1, 0, At, B0); PG8_MMA(1, 1, At, B1); PG8_BAR; PG8_SCHED;
	s_add_i32 s18, s18, s27
	v_lshl_add_u64 v[194:195], v[194:195], 0, s[30:31]
	s_mov_b32 m0, s18
	ds_read_b128 v[178:181], v144 offset:49152
	ds_read_b128 v[182:185], v144 offset:50176
	ds_read_b128 v[186:189], v144 offset:51200
	ds_read_b128 v[190:193], v144 offset:52224
	ds_read_b128 v[202:205], v144 offset:53248
	ds_read_b128 v[206:209], v144 offset:54272
	ds_read_b128 v[210:213], v144 offset:55296
	ds_read_b128 v[214:217], v144 offset:56320
	global_load_lds_dwordx4 v[194:195], off
	s_add_i32 m0, s18, 0x2000
	s_add_u32 s38, s56, 0x40080
	v_lshl_add_u64 v[194:195], v[218:219], 0, s[30:31]
	s_addc_u32 s39, s57, 0
	s_add_i32 s18, s83, s27
	global_load_lds_dwordx4 v[194:195], off
	v_lshl_add_u64 v[194:195], s[38:39], 0, v[0:1]
	s_mov_b32 m0, s18
	s_nop 0
	global_load_lds_dwordx4 v[194:195], off
	v_lshl_add_u64 v[194:195], s[38:39], 0, v[130:131]
	s_add_i32 m0, s18, 0x2000
	s_nop 0
	global_load_lds_dwordx4 v[194:195], off
	v_lshl_add_u64 v[194:195], v[220:221], 0, s[30:31]
	s_mov_b32 m0, s71
	s_nop 0
	global_load_lds_dwordx4 v[194:195], off
	v_lshl_add_u64 v[194:195], v[222:223], 0, s[30:31]
	s_mov_b32 m0, s72
	s_nop 0
	global_load_lds_dwordx4 v[194:195], off
	s_waitcnt vmcnt(8)
	s_waitcnt lgkmcnt(0)
	s_barrier
	s_setprio 1
	s_waitcnt lgkmcnt(0)
	v_mfma_f32_16x16x32_bf16 v[50:53], v[146:149], v[178:181], v[50:53]
	v_mfma_f32_16x16x32_bf16 v[50:53], v[150:153], v[182:185], v[50:53]
	v_mfma_f32_16x16x32_bf16 v[54:57], v[154:157], v[178:181], v[54:57]
	v_mfma_f32_16x16x32_bf16 v[54:57], v[158:161], v[182:185], v[54:57]
	v_mfma_f32_16x16x32_bf16 v[58:61], v[162:165], v[178:181], v[58:61]
	v_mfma_f32_16x16x32_bf16 v[58:61], v[166:169], v[182:185], v[58:61]
	v_mfma_f32_16x16x32_bf16 v[62:65], v[170:173], v[178:181], v[62:65]
	v_mfma_f32_16x16x32_bf16 v[62:65], v[174:177], v[182:185], v[62:65]
	v_mfma_f32_16x16x32_bf16 v[34:37], v[146:149], v[186:189], v[34:37]
	v_mfma_f32_16x16x32_bf16 v[34:37], v[150:153], v[190:193], v[34:37]
	v_mfma_f32_16x16x32_bf16 v[38:41], v[154:157], v[186:189], v[38:41]
	v_mfma_f32_16x16x32_bf16 v[38:41], v[158:161], v[190:193], v[38:41]
	v_mfma_f32_16x16x32_bf16 v[42:45], v[162:165], v[186:189], v[42:45]
	v_mfma_f32_16x16x32_bf16 v[42:45], v[166:169], v[190:193], v[42:45]
	v_mfma_f32_16x16x32_bf16 v[46:49], v[170:173], v[186:189], v[46:49]
	v_mfma_f32_16x16x32_bf16 v[46:49], v[174:177], v[190:193], v[46:49]
	v_mfma_f32_16x16x32_bf16 v[18:21], v[146:149], v[202:205], v[18:21]
	v_mfma_f32_16x16x32_bf16 v[18:21], v[150:153], v[206:209], v[18:21]
	v_mfma_f32_16x16x32_bf16 v[22:25], v[154:157], v[202:205], v[22:25]
	v_mfma_f32_16x16x32_bf16 v[22:25], v[158:161], v[206:209], v[22:25]
	v_mfma_f32_16x16x32_bf16 v[26:29], v[162:165], v[202:205], v[26:29]
	v_mfma_f32_16x16x32_bf16 v[26:29], v[166:169], v[206:209], v[26:29]
	v_mfma_f32_16x16x32_bf16 v[30:33], v[170:173], v[202:205], v[30:33]
	v_mfma_f32_16x16x32_bf16 v[30:33], v[174:177], v[206:209], v[30:33]
	v_mfma_f32_16x16x32_bf16 v[2:5], v[146:149], v[210:213], v[2:5]
	v_mfma_f32_16x16x32_bf16 v[2:5], v[150:153], v[214:217], v[2:5]
	v_mfma_f32_16x16x32_bf16 v[6:9], v[154:157], v[210:213], v[6:9]
	v_mfma_f32_16x16x32_bf16 v[6:9], v[158:161], v[214:217], v[6:9]
	v_mfma_f32_16x16x32_bf16 v[10:13], v[162:165], v[210:213], v[10:13]
	v_mfma_f32_16x16x32_bf16 v[10:13], v[166:169], v[214:217], v[10:13]
	v_mfma_f32_16x16x32_bf16 v[14:17], v[170:173], v[210:213], v[14:17]
	v_mfma_f32_16x16x32_bf16 v[14:17], v[174:177], v[214:217], v[14:17]
	s_setprio 0
	s_barrier
	s_add_i32 s82, s82, 2
	s_add_u32 s60, s60, 0x100
	s_addc_u32 s61, s61, 0
	s_add_u32 s80, s80, 0x100
	s_addc_u32 s81, s81, 0
	s_cmp_gt_u32 s82, 13
	s_cbranch_scc0 .LBB0_220
	s_and_b64 vcc, exec, s[44:45]
	s_cbranch_vccz .LBB0_223
	s_barrier

; #define PG8_STAGE(bufoff, gbase, voff) do { _Pragma("unroll") for (int _i = 0; _i < 2; ++_i) \
;         __builtin_amdgcn_global_load_lds((const unsigned*)((const char*)(gbase) + (voff)[_i]), (PG8_LAS unsigned*)(lds + (bufoff) + ldsw + _i * 8192), 16, 0, 0); } while (0)
; #define PG8_LDA(dst, b, h) do { _Pragma("unroll") for (int m = 0; m < 4; ++m) _Pragma("unroll") for (int k = 0; k < 2; ++k) dst[m][k] = *(const PG8_LAS bf16x8*)(lds + PG8_SA(b, h) + aoff + m * 2048 + k * 1024); } while (0)
; #define PG8_LDB(dst, b, h) do { _Pragma("unroll") for (int n = 0; n < 2; ++n) _Pragma("unroll") for (int k = 0; k < 2; ++k) dst[n][k] = *(const PG8_LAS bf16x8*)(lds + PG8_SB(b, h) + boff + n * 2048 + k * 1024); } while (0)
; #define PG8_MMA(ai, bj, At, Bt) do { __builtin_amdgcn_s_setprio(1); _Pragma("unroll") for (int m = 0; m < 4; ++m) _Pragma("unroll") for (int n = 0; n < 2; ++n) _Pragma("unroll") for (int k = 0; k < 2; ++k) \
;         acc[ai][bj][m][n] = __builtin_amdgcn_mfma_f32_16x16x32_bf16(Bt[n][k], At[m][k], acc[ai][bj][m][n], 0, 0, 0); __builtin_amdgcn_s_setprio(0); } while (0)
; #define PG8_WAIT_V(n) asm volatile("s_waitcnt vmcnt(" #n ")" ::: "memory")
; #define PG8_WAIT_L(n) asm volatile("s_waitcnt lgkmcnt(" #n ")" ::: "memory")
; #define PG8_BAR __builtin_amdgcn_s_barrier()
; #define PG8_SCHED __builtin_amdgcn_sched_barrier(0)
; template <class Epi, class Sched, bool ALIGN_EPI = false, bool SP2 = false>
; __device__ __forceinline__ void gemm_phase(PG8_LAS unsigned char* lds, const Gemm g, const Sched& S, const Epi& E) {
;     ...
;         for (int t = 0; t < nt; t += 2) {
;             const bool last = (t == nt - 2);
;             const char* a1 = cA + (size_t)(t + 1) * kstep;
;             const char* a2 = last ? nA : cA + (size_t)(t + 2) * kstep; const char* b2 = last ? nB : cB + (size_t)(t + 2) * kstep;
;             const char* a3 = a2 + kstep; const char* b3 = b2 + kstep;
;             if (last && has_next) S.a_ready(nxt);
;             if constexpr (SP2) {
;             PG8_LDB(B0, 0, 0); PG8_LDB(B1, 0, 1); PG8_SCHED; PG8_LDA(At, 0, 0); PG8_STAGE(PG8_SA(1, 1), a1 + hstep, voffA);
;             PG8_WAIT_V(8); PG8_WAIT_L(0); PG8_BAR; PG8_MMA(0, 0, At, B0); PG8_MMA(0, 1, At, B1); PG8_BAR; PG8_SCHED;
;             PG8_LDA(At, 0, 1); PG8_STAGE(PG8_SB(0, 0), b2, voffB); PG8_STAGE(PG8_SB(0, 1), b2 + hstep, voffB); PG8_STAGE(PG8_SA(0, 0), a2, voffA);
.LBB0_274:
	s_add_i32 vcc_lo, s46, 2
	s_add_u32 s38, s48, 0x80
	s_addc_u32 s39, s49, 0
	s_add_i32 vcc_hi, 0, 0x10000
	s_cmp_eq_u32 s99, s46
	s_cselect_b32 s47, s81, s39
	s_cselect_b32 s46, s80, s38
	s_cselect_b32 s39, s83, s51
	s_cselect_b32 s38, s82, s50
	s_add_i32 s18, 0, 0x14000
	v_add_u32_e32 v142, vcc_hi, v245
	v_add_u32_e32 v158, s18, v245
	ds_read_b128 v[110:113], v142
	ds_read_b128 v[118:121], v142 offset:1024
	ds_read_b128 v[138:141], v142 offset:2048
	ds_read_b128 v[142:145], v142 offset:3072
	ds_read_b128 v[146:149], v158
	ds_read_b128 v[150:153], v158 offset:1024
	ds_read_b128 v[154:157], v158 offset:2048
	ds_read_b128 v[158:161], v158 offset:3072
	v_lshl_add_u64 v[210:211], s[48:49], 0, v[206:207]
	s_add_i32 m0, s92, 0xc000
	ds_read_b128 v[162:165], v247
	ds_read_b128 v[166:169], v247 offset:1024
	ds_read_b128 v[170:173], v247 offset:2048
	ds_read_b128 v[174:177], v247 offset:3072
	ds_read_b128 v[178:181], v247 offset:4096
	ds_read_b128 v[182:185], v247 offset:5120
	ds_read_b128 v[186:189], v247 offset:6144
	ds_read_b128 v[190:193], v247 offset:7168
	global_load_lds_dwordx4 v[210:211], off
	v_lshl_add_u64 v[210:211], s[48:49], 0, v[208:209]
	s_add_i32 m0, s92, 0xe000
	s_nop 0
	global_load_lds_dwordx4 v[210:211], off
	s_waitcnt vmcnt(8)
	s_waitcnt lgkmcnt(0)
	s_barrier
	s_setprio 1
	s_waitcnt lgkmcnt(0)
	v_mfma_f32_16x16x32_bf16 v[130:133], v[110:113], v[162:165], v[130:133]
	v_mfma_f32_16x16x32_bf16 v[130:133], v[118:121], v[166:169], v[130:133]
	v_mfma_f32_16x16x32_bf16 v[134:137], v[138:141], v[162:165], v[134:137]
	v_mfma_f32_16x16x32_bf16 v[134:137], v[142:145], v[166:169], v[134:137]
	v_mfma_f32_16x16x32_bf16 v[126:129], v[146:149], v[162:165], v[126:129]
	v_mfma_f32_16x16x32_bf16 v[126:129], v[150:153], v[166:169], v[126:129]
	v_mfma_f32_16x16x32_bf16 v[122:125], v[154:157], v[162:165], v[122:125]
	v_mfma_f32_16x16x32_bf16 v[122:125], v[158:161], v[166:169], v[122:125]
	v_mfma_f32_16x16x32_bf16 v[114:117], v[110:113], v[170:173], v[114:117]
	v_mfma_f32_16x16x32_bf16 v[114:117], v[118:121], v[174:177], v[114:117]
	v_mfma_f32_16x16x32_bf16 v[106:109], v[138:141], v[170:173], v[106:109]
	v_mfma_f32_16x16x32_bf16 v[106:109], v[142:145], v[174:177], v[106:109]
	v_mfma_f32_16x16x32_bf16 v[102:105], v[146:149], v[170:173], v[102:105]
	v_mfma_f32_16x16x32_bf16 v[102:105], v[150:153], v[174:177], v[102:105]
	v_mfma_f32_16x16x32_bf16 v[98:101], v[154:157], v[170:173], v[98:101]
	v_mfma_f32_16x16x32_bf16 v[98:101], v[158:161], v[174:177], v[98:101]
	v_mfma_f32_16x16x32_bf16 v[94:97], v[110:113], v[178:181], v[94:97]
	v_mfma_f32_16x16x32_bf16 v[94:97], v[118:121], v[182:185], v[94:97]
	v_mfma_f32_16x16x32_bf16 v[90:93], v[138:141], v[178:181], v[90:93]
	v_mfma_f32_16x16x32_bf16 v[90:93], v[142:145], v[182:185], v[90:93]
	v_mfma_f32_16x16x32_bf16 v[86:89], v[146:149], v[178:181], v[86:89]
	v_mfma_f32_16x16x32_bf16 v[86:89], v[150:153], v[182:185], v[86:89]
	v_mfma_f32_16x16x32_bf16 v[82:85], v[154:157], v[178:181], v[82:85]
	v_mfma_f32_16x16x32_bf16 v[82:85], v[158:161], v[182:185], v[82:85]
	v_mfma_f32_16x16x32_bf16 v[78:81], v[110:113], v[186:189], v[78:81]
	v_mfma_f32_16x16x32_bf16 v[78:81], v[118:121], v[190:193], v[78:81]
	v_mfma_f32_16x16x32_bf16 v[74:77], v[138:141], v[186:189], v[74:77]
	v_mfma_f32_16x16x32_bf16 v[74:77], v[142:145], v[190:193], v[74:77]
	v_mfma_f32_16x16x32_bf16 v[70:73], v[146:149], v[186:189], v[70:73]
	v_mfma_f32_16x16x32_bf16 v[70:73], v[150:153], v[190:193], v[70:73]
	v_mfma_f32_16x16x32_bf16 v[66:69], v[154:157], v[186:189], v[66:69]
	v_mfma_f32_16x16x32_bf16 v[66:69], v[158:161], v[190:193], v[66:69]
	s_setprio 0
	s_barrier
	s_add_i32 vcc_hi, vcc_hi, s6
	v_lshl_add_u64 v[210:211], s[38:39], 0, v[0:1]
	s_mov_b32 m0, vcc_hi
	ds_read_b128 v[162:165], v247 offset:16384
	ds_read_b128 v[166:169], v247 offset:17408
	ds_read_b128 v[170:173], v247 offset:18432
	ds_read_b128 v[174:177], v247 offset:19456
	ds_read_b128 v[178:181], v247 offset:20480
	ds_read_b128 v[182:185], v247 offset:21504
	ds_read_b128 v[186:189], v247 offset:22528
	ds_read_b128 v[190:193], v247 offset:23552
	global_load_lds_dwordx4 v[210:211], off
	s_add_i32 m0, vcc_hi, 0x2000
	v_lshl_add_u64 v[212:213], s[38:39], 0, v[204:205]
	s_add_u32 s38, s38, s58
	s_addc_u32 s39, s39, 0
	s_add_i32 s18, s18, s6
	global_load_lds_dwordx4 v[212:213], off
	v_lshl_add_u64 v[214:215], s[38:39], 0, v[0:1]
	s_mov_b32 m0, s18
	v_lshl_add_u64 v[216:217], s[38:39], 0, v[204:205]
	global_load_lds_dwordx4 v[214:215], off
	s_add_i32 m0, s18, 0x2000
	v_lshl_add_u64 v[218:219], s[46:47], 0, v[194:195]
	global_load_lds_dwordx4 v[216:217], off
	s_mov_b32 m0, s92
	v_lshl_add_u64 v[220:221], s[46:47], 0, v[202:203]
	global_load_lds_dwordx4 v[218:219], off
	s_mov_b32 m0, s93
	s_nop 0
	global_load_lds_dwordx4 v[220:221], off
	s_waitcnt vmcnt(8)
	s_waitcnt lgkmcnt(0)
	s_barrier
; #define PG8_STAGE(bufoff, gbase, voff) do { _Pragma("unroll") for (int _i = 0; _i < 2; ++_i) \
;         __builtin_amdgcn_global_load_lds((const unsigned*)((const char*)(gbase) + (voff)[_i]), (PG8_LAS unsigned*)(lds + (bufoff) + ldsw + _i * 8192), 16, 0, 0); } while (0)
; #define PG8_LDA(dst, b, h) do { _Pragma("unroll") for (int m = 0; m < 4; ++m) _Pragma("unroll") for (int k = 0; k < 2; ++k) dst[m][k] = *(const PG8_LAS bf16x8*)(lds + PG8_SA(b, h) + aoff + m * 2048 + k * 1024); } while (0)
; #define PG8_LDB(dst, b, h) do { _Pragma("unroll") for (int n = 0; n < 2; ++n) _Pragma("unroll") for (int k = 0; k < 2; ++k) dst[n][k] = *(const PG8_LAS bf16x8*)(lds + PG8_SB(b, h) + boff + n * 2048 + k * 1024); } while (0)
; #define PG8_MMA(ai, bj, At, Bt) do { __builtin_amdgcn_s_setprio(1); _Pragma("unroll") for (int m = 0; m < 4; ++m) _Pragma("unroll") for (int n = 0; n < 2; ++n) _Pragma("unroll") for (int k = 0; k < 2; ++k) \
;         acc[ai][bj][m][n] = __builtin_amdgcn_mfma_f32_16x16x32_bf16(Bt[n][k], At[m][k], acc[ai][bj][m][n], 0, 0, 0); __builtin_amdgcn_s_setprio(0); } while (0)
; #define PG8_WAIT_V(n) asm volatile("s_waitcnt vmcnt(" #n ")" ::: "memory")
; #define PG8_WAIT_L(n) asm volatile("s_waitcnt lgkmcnt(" #n ")" ::: "memory")
; #define PG8_BAR __builtin_amdgcn_s_barrier()
; #define PG8_SCHED __builtin_amdgcn_sched_barrier(0)
; template <class Epi, class Sched, bool ALIGN_EPI = false, bool SP2 = false>
; __device__ __forceinline__ void gemm_phase(PG8_LAS unsigned char* lds, const Gemm g, const Sched& S, const Epi& E) {
;     ...
;             PG8_WAIT_V(8); PG8_WAIT_L(0); PG8_BAR; PG8_MMA(1, 0, At, B0); PG8_MMA(1, 1, At, B1); PG8_BAR; PG8_SCHED;
;             PG8_LDB(B0, 1, 0); PG8_LDB(B1, 1, 1); PG8_SCHED; PG8_LDA(At, 1, 0); PG8_STAGE(PG8_SA(0, 1), a2 + hstep, voffA);
;             PG8_WAIT_V(8); PG8_WAIT_L(0); PG8_BAR; PG8_MMA(0, 0, At, B0); PG8_MMA(0, 1, At, B1); PG8_BAR; PG8_SCHED;
	s_setprio 1
	s_waitcnt lgkmcnt(0)
	v_mfma_f32_16x16x32_bf16 v[62:65], v[110:113], v[162:165], v[62:65]
	v_mfma_f32_16x16x32_bf16 v[62:65], v[118:121], v[166:169], v[62:65]
	v_mfma_f32_16x16x32_bf16 v[58:61], v[138:141], v[162:165], v[58:61]
	v_mfma_f32_16x16x32_bf16 v[58:61], v[142:145], v[166:169], v[58:61]
	v_mfma_f32_16x16x32_bf16 v[54:57], v[146:149], v[162:165], v[54:57]
	v_mfma_f32_16x16x32_bf16 v[54:57], v[150:153], v[166:169], v[54:57]
	v_mfma_f32_16x16x32_bf16 v[50:53], v[154:157], v[162:165], v[50:53]
	v_mfma_f32_16x16x32_bf16 v[50:53], v[158:161], v[166:169], v[50:53]
	v_mfma_f32_16x16x32_bf16 v[46:49], v[110:113], v[170:173], v[46:49]
	v_mfma_f32_16x16x32_bf16 v[46:49], v[118:121], v[174:177], v[46:49]
	v_mfma_f32_16x16x32_bf16 v[42:45], v[138:141], v[170:173], v[42:45]
	v_mfma_f32_16x16x32_bf16 v[42:45], v[142:145], v[174:177], v[42:45]
	v_mfma_f32_16x16x32_bf16 v[38:41], v[146:149], v[170:173], v[38:41]
	v_mfma_f32_16x16x32_bf16 v[38:41], v[150:153], v[174:177], v[38:41]
	v_mfma_f32_16x16x32_bf16 v[34:37], v[154:157], v[170:173], v[34:37]
	v_mfma_f32_16x16x32_bf16 v[34:37], v[158:161], v[174:177], v[34:37]
	v_mfma_f32_16x16x32_bf16 v[30:33], v[110:113], v[178:181], v[30:33]
	v_mfma_f32_16x16x32_bf16 v[30:33], v[118:121], v[182:185], v[30:33]
	v_mfma_f32_16x16x32_bf16 v[26:29], v[138:141], v[178:181], v[26:29]
	v_mfma_f32_16x16x32_bf16 v[26:29], v[142:145], v[182:185], v[26:29]
	v_mfma_f32_16x16x32_bf16 v[22:25], v[146:149], v[178:181], v[22:25]
	v_mfma_f32_16x16x32_bf16 v[22:25], v[150:153], v[182:185], v[22:25]
	v_mfma_f32_16x16x32_bf16 v[18:21], v[154:157], v[178:181], v[18:21]
	v_mfma_f32_16x16x32_bf16 v[18:21], v[158:161], v[182:185], v[18:21]
	v_mfma_f32_16x16x32_bf16 v[14:17], v[110:113], v[186:189], v[14:17]
	v_mfma_f32_16x16x32_bf16 v[14:17], v[118:121], v[190:193], v[14:17]
	v_mfma_f32_16x16x32_bf16 v[10:13], v[138:141], v[186:189], v[10:13]
	v_mfma_f32_16x16x32_bf16 v[10:13], v[142:145], v[190:193], v[10:13]
	v_mfma_f32_16x16x32_bf16 v[6:9], v[146:149], v[186:189], v[6:9]
	v_mfma_f32_16x16x32_bf16 v[6:9], v[150:153], v[190:193], v[6:9]
	v_mfma_f32_16x16x32_bf16 v[2:5], v[154:157], v[186:189], v[2:5]
	v_mfma_f32_16x16x32_bf16 v[2:5], v[158:161], v[190:193], v[2:5]
	s_setprio 0
	s_barrier
	s_add_i32 s18, 0, 0x18000
	s_add_i32 vcc_hi, 0, 0x1c000
	v_add_u32_e32 v142, s18, v245
	v_add_u32_e32 v158, vcc_hi, v245
	ds_read_b128 v[110:113], v142
	ds_read_b128 v[118:121], v142 offset:1024
	ds_read_b128 v[138:141], v142 offset:2048
	ds_read_b128 v[142:145], v142 offset:3072
	ds_read_b128 v[146:149], v158
	ds_read_b128 v[150:153], v158 offset:1024
	ds_read_b128 v[154:157], v158 offset:2048
	ds_read_b128 v[158:161], v158 offset:3072
	s_add_u32 s38, s46, s58
	s_addc_u32 s39, s47, 0
	s_mov_b32 m0, s94
	v_lshl_add_u64 v[222:223], s[38:39], 0, v[194:195]
	ds_read_b128 v[162:165], v247 offset:32768
	ds_read_b128 v[166:169], v247 offset:33792
	ds_read_b128 v[170:173], v247 offset:34816
	ds_read_b128 v[174:177], v247 offset:35840
	ds_read_b128 v[178:181], v247 offset:36864
	ds_read_b128 v[182:185], v247 offset:37888
	ds_read_b128 v[186:189], v247 offset:38912
	ds_read_b128 v[190:193], v247 offset:39936
	global_load_lds_dwordx4 v[222:223], off
	v_lshl_add_u64 v[222:223], s[38:39], 0, v[202:203]
	s_mov_b32 m0, s95
	s_nop 0
	global_load_lds_dwordx4 v[222:223], off
	s_waitcnt vmcnt(8)
	s_waitcnt lgkmcnt(0)
	s_barrier
	s_setprio 1
	s_waitcnt lgkmcnt(0)
	v_mfma_f32_16x16x32_bf16 v[130:133], v[110:113], v[162:165], v[130:133]
	v_mfma_f32_16x16x32_bf16 v[130:133], v[118:121], v[166:169], v[130:133]
	v_mfma_f32_16x16x32_bf16 v[134:137], v[138:141], v[162:165], v[134:137]
	v_mfma_f32_16x16x32_bf16 v[134:137], v[142:145], v[166:169], v[134:137]
	v_mfma_f32_16x16x32_bf16 v[126:129], v[146:149], v[162:165], v[126:129]
	v_mfma_f32_16x16x32_bf16 v[126:129], v[150:153], v[166:169], v[126:129]
	v_mfma_f32_16x16x32_bf16 v[122:125], v[154:157], v[162:165], v[122:125]
	v_mfma_f32_16x16x32_bf16 v[122:125], v[158:161], v[166:169], v[122:125]
	v_mfma_f32_16x16x32_bf16 v[114:117], v[110:113], v[170:173], v[114:117]
	v_mfma_f32_16x16x32_bf16 v[114:117], v[118:121], v[174:177], v[114:117]
	v_mfma_f32_16x16x32_bf16 v[106:109], v[138:141], v[170:173], v[106:109]
	v_mfma_f32_16x16x32_bf16 v[106:109], v[142:145], v[174:177], v[106:109]
	v_mfma_f32_16x16x32_bf16 v[102:105], v[146:149], v[170:173], v[102:105]
	v_mfma_f32_16x16x32_bf16 v[102:105], v[150:153], v[174:177], v[102:105]
	v_mfma_f32_16x16x32_bf16 v[98:101], v[154:157], v[170:173], v[98:101]
	v_mfma_f32_16x16x32_bf16 v[98:101], v[158:161], v[174:177], v[98:101]
	v_mfma_f32_16x16x32_bf16 v[94:97], v[110:113], v[178:181], v[94:97]
	v_mfma_f32_16x16x32_bf16 v[94:97], v[118:121], v[182:185], v[94:97]
	v_mfma_f32_16x16x32_bf16 v[90:93], v[138:141], v[178:181], v[90:93]
	v_mfma_f32_16x16x32_bf16 v[90:93], v[142:145], v[182:185], v[90:93]
	v_mfma_f32_16x16x32_bf16 v[86:89], v[146:149], v[178:181], v[86:89]
	v_mfma_f32_16x16x32_bf16 v[86:89], v[150:153], v[182:185], v[86:89]
	v_mfma_f32_16x16x32_bf16 v[82:85], v[154:157], v[178:181], v[82:85]
	v_mfma_f32_16x16x32_bf16 v[82:85], v[158:161], v[182:185], v[82:85]
	v_mfma_f32_16x16x32_bf16 v[78:81], v[110:113], v[186:189], v[78:81]
	v_mfma_f32_16x16x32_bf16 v[78:81], v[118:121], v[190:193], v[78:81]
	v_mfma_f32_16x16x32_bf16 v[74:77], v[138:141], v[186:189], v[74:77]
	v_mfma_f32_16x16x32_bf16 v[74:77], v[142:145], v[190:193], v[74:77]
	v_mfma_f32_16x16x32_bf16 v[70:73], v[146:149], v[186:189], v[70:73]
	v_mfma_f32_16x16x32_bf16 v[70:73], v[150:153], v[190:193], v[70:73]
	v_mfma_f32_16x16x32_bf16 v[66:69], v[154:157], v[186:189], v[66:69]
	v_mfma_f32_16x16x32_bf16 v[66:69], v[158:161], v[190:193], v[66:69]
	s_setprio 0
	s_barrier
; #define PG8_STAGE(bufoff, gbase, voff) do { _Pragma("unroll") for (int _i = 0; _i < 2; ++_i) \
;         __builtin_amdgcn_global_load_lds((const unsigned*)((const char*)(gbase) + (voff)[_i]), (PG8_LAS unsigned*)(lds + (bufoff) + ldsw + _i * 8192), 16, 0, 0); } while (0)
; #define PG8_LDA(dst, b, h) do { _Pragma("unroll") for (int m = 0; m < 4; ++m) _Pragma("unroll") for (int k = 0; k < 2; ++k) dst[m][k] = *(const PG8_LAS bf16x8*)(lds + PG8_SA(b, h) + aoff + m * 2048 + k * 1024); } while (0)
; #define PG8_LDB(dst, b, h) do { _Pragma("unroll") for (int n = 0; n < 2; ++n) _Pragma("unroll") for (int k = 0; k < 2; ++k) dst[n][k] = *(const PG8_LAS bf16x8*)(lds + PG8_SB(b, h) + boff + n * 2048 + k * 1024); } while (0)
; template <class Epi, class Sched, bool ALIGN_EPI = false, bool SP2 = false>
; __device__ __forceinline__ void gemm_phase(PG8_LAS unsigned char* lds, const Gemm g, const Sched& S, const Epi& E) {
;     ...
;         for (int t = 0; t < nt; t += 2) {
;             const bool last = (t == nt - 2);
;             const char* a1 = cA + (size_t)(t + 1) * kstep;
;             const char* a2 = last ? nA : cA + (size_t)(t + 2) * kstep; const char* b2 = last ? nB : cB + (size_t)(t + 2) * kstep;
;             const char* a3 = a2 + kstep; const char* b3 = b2 + kstep;
;             if (last && has_next) S.a_ready(nxt);
;             if constexpr (SP2) {
;             PG8_LDB(B0, 0, 0); PG8_LDB(B1, 0, 1); PG8_SCHED; PG8_LDA(At, 0, 0); PG8_STAGE(PG8_SA(1, 1), a1 + hstep, voffA);
;             PG8_WAIT_V(8); PG8_WAIT_L(0); PG8_BAR; PG8_MMA(0, 0, At, B0); PG8_MMA(0, 1, At, B1); PG8_BAR; PG8_SCHED;
;             PG8_LDA(At, 0, 1); PG8_STAGE(PG8_SB(0, 0), b2, voffB); PG8_STAGE(PG8_SB(0, 1), b2 + hstep, voffB); PG8_STAGE(PG8_SA(0, 0), a2, voffA);
;             PG8_WAIT_V(8); PG8_WAIT_L(0); PG8_BAR; PG8_MMA(1, 0, At, B0); PG8_MMA(1, 1, At, B1); PG8_BAR; PG8_SCHED;
;             PG8_LDB(B0, 1, 0); PG8_LDB(B1, 1, 1); PG8_SCHED; PG8_LDA(At, 1, 0); PG8_STAGE(PG8_SA(0, 1), a2 + hstep, voffA);
;             PG8_WAIT_V(8); PG8_WAIT_L(0); PG8_BAR; PG8_MMA(0, 0, At, B0); PG8_MMA(0, 1, At, B1); PG8_BAR; PG8_SCHED;
;             PG8_LDA(At, 1, 1); PG8_STAGE(PG8_SB(1, 0), b3, voffB); PG8_STAGE(PG8_SB(1, 1), b3 + hstep, voffB); PG8_STAGE(PG8_SA(1, 0), a3, voffA);
;             PG8_WAIT_V(8); PG8_WAIT_L(0); PG8_BAR; PG8_MMA(1, 0, At, B0); PG8_MMA(1, 1, At, B1); PG8_BAR; PG8_SCHED;
	s_add_i32 s18, s18, s6
	v_lshl_add_u64 v[210:211], v[210:211], 0, s[30:31]
	s_mov_b32 m0, s18
	ds_read_b128 v[162:165], v247 offset:49152
	ds_read_b128 v[166:169], v247 offset:50176
	ds_read_b128 v[170:173], v247 offset:51200
	ds_read_b128 v[174:177], v247 offset:52224
	ds_read_b128 v[178:181], v247 offset:53248
	ds_read_b128 v[182:185], v247 offset:54272
	ds_read_b128 v[186:189], v247 offset:55296
	ds_read_b128 v[190:193], v247 offset:56320
	global_load_lds_dwordx4 v[210:211], off
	v_lshl_add_u64 v[210:211], v[212:213], 0, s[30:31]
	s_add_i32 m0, s18, 0x2000
	s_add_i32 s18, vcc_hi, s6
	global_load_lds_dwordx4 v[210:211], off
	v_lshl_add_u64 v[210:211], v[214:215], 0, s[30:31]
	s_mov_b32 m0, s18
	s_nop 0
	global_load_lds_dwordx4 v[210:211], off
	v_lshl_add_u64 v[210:211], v[216:217], 0, s[30:31]
	s_add_i32 m0, s18, 0x2000
	s_nop 0
	global_load_lds_dwordx4 v[210:211], off
	v_lshl_add_u64 v[210:211], v[218:219], 0, s[30:31]
	s_mov_b32 m0, s97
	s_nop 0
	global_load_lds_dwordx4 v[210:211], off
	v_lshl_add_u64 v[210:211], v[220:221], 0, s[30:31]
	s_mov_b32 m0, s98
	s_nop 0
	global_load_lds_dwordx4 v[210:211], off
	s_waitcnt vmcnt(8)
	s_waitcnt lgkmcnt(0)
	s_barrier
	s_setprio 1
	s_waitcnt lgkmcnt(0)
	v_mfma_f32_16x16x32_bf16 v[62:65], v[110:113], v[162:165], v[62:65]
	v_mfma_f32_16x16x32_bf16 v[62:65], v[118:121], v[166:169], v[62:65]
	v_mfma_f32_16x16x32_bf16 v[58:61], v[138:141], v[162:165], v[58:61]
	v_mfma_f32_16x16x32_bf16 v[58:61], v[142:145], v[166:169], v[58:61]
	v_mfma_f32_16x16x32_bf16 v[54:57], v[146:149], v[162:165], v[54:57]
	v_mfma_f32_16x16x32_bf16 v[54:57], v[150:153], v[166:169], v[54:57]
	v_mfma_f32_16x16x32_bf16 v[50:53], v[154:157], v[162:165], v[50:53]
	v_mfma_f32_16x16x32_bf16 v[50:53], v[158:161], v[166:169], v[50:53]
	v_mfma_f32_16x16x32_bf16 v[46:49], v[110:113], v[170:173], v[46:49]
	v_mfma_f32_16x16x32_bf16 v[46:49], v[118:121], v[174:177], v[46:49]
	v_mfma_f32_16x16x32_bf16 v[42:45], v[138:141], v[170:173], v[42:45]
	v_mfma_f32_16x16x32_bf16 v[42:45], v[142:145], v[174:177], v[42:45]
	v_mfma_f32_16x16x32_bf16 v[38:41], v[146:149], v[170:173], v[38:41]
	v_mfma_f32_16x16x32_bf16 v[38:41], v[150:153], v[174:177], v[38:41]
	v_mfma_f32_16x16x32_bf16 v[34:37], v[154:157], v[170:173], v[34:37]
	v_mfma_f32_16x16x32_bf16 v[34:37], v[158:161], v[174:177], v[34:37]
	v_mfma_f32_16x16x32_bf16 v[30:33], v[110:113], v[178:181], v[30:33]
	v_mfma_f32_16x16x32_bf16 v[30:33], v[118:121], v[182:185], v[30:33]
	v_mfma_f32_16x16x32_bf16 v[26:29], v[138:141], v[178:181], v[26:29]
	v_mfma_f32_16x16x32_bf16 v[26:29], v[142:145], v[182:185], v[26:29]
	v_mfma_f32_16x16x32_bf16 v[22:25], v[146:149], v[178:181], v[22:25]
	v_mfma_f32_16x16x32_bf16 v[22:25], v[150:153], v[182:185], v[22:25]
	v_mfma_f32_16x16x32_bf16 v[18:21], v[154:157], v[178:181], v[18:21]
	v_mfma_f32_16x16x32_bf16 v[18:21], v[158:161], v[182:185], v[18:21]
	v_mfma_f32_16x16x32_bf16 v[14:17], v[110:113], v[186:189], v[14:17]
	v_mfma_f32_16x16x32_bf16 v[14:17], v[118:121], v[190:193], v[14:17]
	v_mfma_f32_16x16x32_bf16 v[10:13], v[138:141], v[186:189], v[10:13]
	v_mfma_f32_16x16x32_bf16 v[10:13], v[142:145], v[190:193], v[10:13]
	v_mfma_f32_16x16x32_bf16 v[6:9], v[146:149], v[186:189], v[6:9]
	v_mfma_f32_16x16x32_bf16 v[6:9], v[150:153], v[190:193], v[6:9]
	v_mfma_f32_16x16x32_bf16 v[2:5], v[154:157], v[186:189], v[2:5]
	v_mfma_f32_16x16x32_bf16 v[2:5], v[158:161], v[190:193], v[2:5]
	s_setprio 0
	s_barrier
	s_add_u32 s48, s48, 0x100
	s_addc_u32 s49, s49, 0
	s_add_u32 s50, s50, 0x100
	s_addc_u32 s51, s51, 0
	s_cmp_ge_u32 vcc_lo, s96
	s_mov_b32 s46, vcc_lo
	s_cbranch_scc0 .LBB0_274
	s_and_b64 vcc, exec, s[72:73]
	s_cbranch_vccz .LBB0_277
	s_barrier

; #define PG8_STAGE(bufoff, gbase, voff) do { _Pragma("unroll") for (int _i = 0; _i < 2; ++_i) \
;         __builtin_amdgcn_global_load_lds((const unsigned*)((const char*)(gbase) + (voff)[_i]), (PG8_LAS unsigned*)(lds + (bufoff) + ldsw + _i * 8192), 16, 0, 0); } while (0)
; #define PG8_LDA(dst, b, h) do { _Pragma("unroll") for (int m = 0; m < 4; ++m) _Pragma("unroll") for (int k = 0; k < 2; ++k) dst[m][k] = *(const PG8_LAS bf16x8*)(lds + PG8_SA(b, h) + aoff + m * 2048 + k * 1024); } while (0)
; #define PG8_LDB(dst, b, h) do { _Pragma("unroll") for (int n = 0; n < 2; ++n) _Pragma("unroll") for (int k = 0; k < 2; ++k) dst[n][k] = *(const PG8_LAS bf16x8*)(lds + PG8_SB(b, h) + boff + n * 2048 + k * 1024); } while (0)
; #define PG8_MMA(ai, bj, At, Bt) do { __builtin_amdgcn_s_setprio(1); _Pragma("unroll") for (int m = 0; m < 4; ++m) _Pragma("unroll") for (int n = 0; n < 2; ++n) _Pragma("unroll") for (int k = 0; k < 2; ++k) \
;         acc[ai][bj][m][n] = __builtin_amdgcn_mfma_f32_16x16x32_bf16(Bt[n][k], At[m][k], acc[ai][bj][m][n], 0, 0, 0); __builtin_amdgcn_s_setprio(0); } while (0)
; #define PG8_WAIT_V(n) asm volatile("s_waitcnt vmcnt(" #n ")" ::: "memory")
; #define PG8_WAIT_L(n) asm volatile("s_waitcnt lgkmcnt(" #n ")" ::: "memory")
; #define PG8_BAR __builtin_amdgcn_s_barrier()
; #define PG8_SCHED __builtin_amdgcn_sched_barrier(0)
; template <class Epi, class Sched, bool ALIGN_EPI = false, bool SP2 = false>
; __device__ __forceinline__ void gemm_phase(PG8_LAS unsigned char* lds, const Gemm g, const Sched& S, const Epi& E) {
;     ...
;         for (int t = 0; t < nt; t += 2) {
;             const bool last = (t == nt - 2);
;             const char* a1 = cA + (size_t)(t + 1) * kstep;
;             const char* a2 = last ? nA : cA + (size_t)(t + 2) * kstep; const char* b2 = last ? nB : cB + (size_t)(t + 2) * kstep;
;             const char* a3 = a2 + kstep; const char* b3 = b2 + kstep;
;             if (last && has_next) S.a_ready(nxt);
;             if constexpr (SP2) {
;             PG8_LDB(B0, 0, 0); PG8_LDB(B1, 0, 1); PG8_SCHED; PG8_LDA(At, 0, 0); PG8_STAGE(PG8_SA(1, 1), a1 + hstep, voffA);
;             PG8_WAIT_V(8); PG8_WAIT_L(0); PG8_BAR; PG8_MMA(0, 0, At, B0); PG8_MMA(0, 1, At, B1); PG8_BAR; PG8_SCHED;
;             PG8_LDA(At, 0, 1); PG8_STAGE(PG8_SB(0, 0), b2, voffB); PG8_STAGE(PG8_SB(0, 1), b2 + hstep, voffB); PG8_STAGE(PG8_SA(0, 0), a2, voffA);
.LBB0_408:
	s_add_u32 s38, s48, 0xfffc0080
	s_addc_u32 s39, s49, -1
	s_add_i32 s85, 0, 0x10000
	s_cmp_eq_u32 s84, 12
	s_cselect_b32 s73, s21, s39
	s_cselect_b32 s72, s27, s38
	v_add_u32_e32 v0, s85, v167
	s_cselect_b32 s47, s29, s69
	s_cselect_b32 s46, s33, s53
	s_add_i32 s38, 0, 0x14000
	ds_read_b128 v[142:145], v0
	ds_read_b128 v[146:149], v0 offset:1024
	ds_read_b128 v[150:153], v0 offset:2048
	ds_read_b128 v[154:157], v0 offset:3072
	v_add_u32_e32 v0, s38, v167
	ds_read_b128 v[158:161], v0
	ds_read_b128 v[162:165], v0 offset:1024
	ds_read_b128 v[172:175], v0 offset:2048
	ds_read_b128 v[176:179], v0 offset:3072
	v_lshl_add_u64 v[218:219], s[48:49], 0, v[138:139]
	s_add_i32 m0, s76, 0xc000
	ds_read_b128 v[180:183], v170
	ds_read_b128 v[184:187], v170 offset:1024
	ds_read_b128 v[188:191], v170 offset:2048
	ds_read_b128 v[192:195], v170 offset:3072
	ds_read_b128 v[202:205], v170 offset:4096
	ds_read_b128 v[206:209], v170 offset:5120
	ds_read_b128 v[210:213], v170 offset:6144
	ds_read_b128 v[214:217], v170 offset:7168
	global_load_lds_dwordx4 v[218:219], off
	v_lshl_add_u64 v[218:219], s[48:49], 0, v[140:141]
	s_add_i32 m0, s76, 0xe000
	s_nop 0
	global_load_lds_dwordx4 v[218:219], off
	s_waitcnt vmcnt(8)
	s_waitcnt lgkmcnt(0)
	s_barrier
	s_setprio 1
	s_waitcnt lgkmcnt(0)
	v_mfma_f32_16x16x32_bf16 v[122:125], v[142:145], v[180:183], v[122:125]
	v_mfma_f32_16x16x32_bf16 v[122:125], v[146:149], v[184:187], v[122:125]
	v_mfma_f32_16x16x32_bf16 v[126:129], v[150:153], v[180:183], v[126:129]
	v_mfma_f32_16x16x32_bf16 v[126:129], v[154:157], v[184:187], v[126:129]
	v_mfma_f32_16x16x32_bf16 v[114:117], v[158:161], v[180:183], v[114:117]
	v_mfma_f32_16x16x32_bf16 v[114:117], v[162:165], v[184:187], v[114:117]
	v_mfma_f32_16x16x32_bf16 v[118:121], v[172:175], v[180:183], v[118:121]
	v_mfma_f32_16x16x32_bf16 v[118:121], v[176:179], v[184:187], v[118:121]
	v_mfma_f32_16x16x32_bf16 v[106:109], v[142:145], v[188:191], v[106:109]
	v_mfma_f32_16x16x32_bf16 v[106:109], v[146:149], v[192:195], v[106:109]
	v_mfma_f32_16x16x32_bf16 v[110:113], v[150:153], v[188:191], v[110:113]
	v_mfma_f32_16x16x32_bf16 v[110:113], v[154:157], v[192:195], v[110:113]
	v_mfma_f32_16x16x32_bf16 v[98:101], v[158:161], v[188:191], v[98:101]
	v_mfma_f32_16x16x32_bf16 v[98:101], v[162:165], v[192:195], v[98:101]
	v_mfma_f32_16x16x32_bf16 v[102:105], v[172:175], v[188:191], v[102:105]
	v_mfma_f32_16x16x32_bf16 v[102:105], v[176:179], v[192:195], v[102:105]
	v_mfma_f32_16x16x32_bf16 v[90:93], v[142:145], v[202:205], v[90:93]
	v_mfma_f32_16x16x32_bf16 v[90:93], v[146:149], v[206:209], v[90:93]
	v_mfma_f32_16x16x32_bf16 v[94:97], v[150:153], v[202:205], v[94:97]
	v_mfma_f32_16x16x32_bf16 v[94:97], v[154:157], v[206:209], v[94:97]
	v_mfma_f32_16x16x32_bf16 v[82:85], v[158:161], v[202:205], v[82:85]
	v_mfma_f32_16x16x32_bf16 v[82:85], v[162:165], v[206:209], v[82:85]
	v_mfma_f32_16x16x32_bf16 v[86:89], v[172:175], v[202:205], v[86:89]
	v_mfma_f32_16x16x32_bf16 v[86:89], v[176:179], v[206:209], v[86:89]
	v_mfma_f32_16x16x32_bf16 v[74:77], v[142:145], v[210:213], v[74:77]
	v_mfma_f32_16x16x32_bf16 v[74:77], v[146:149], v[214:217], v[74:77]
	v_mfma_f32_16x16x32_bf16 v[78:81], v[150:153], v[210:213], v[78:81]
	v_mfma_f32_16x16x32_bf16 v[78:81], v[154:157], v[214:217], v[78:81]
	v_mfma_f32_16x16x32_bf16 v[66:69], v[158:161], v[210:213], v[66:69]
	v_mfma_f32_16x16x32_bf16 v[66:69], v[162:165], v[214:217], v[66:69]
	v_mfma_f32_16x16x32_bf16 v[70:73], v[172:175], v[210:213], v[70:73]
	v_mfma_f32_16x16x32_bf16 v[70:73], v[176:179], v[214:217], v[70:73]
	s_setprio 0
	s_barrier
	s_add_i32 s39, s85, s75
	v_lshl_add_u64 v[218:219], s[46:47], 0, v[134:135]
	s_mov_b32 m0, s39
	ds_read_b128 v[180:183], v170 offset:16384
	ds_read_b128 v[184:187], v170 offset:17408
	ds_read_b128 v[188:191], v170 offset:18432
	ds_read_b128 v[192:195], v170 offset:19456
	ds_read_b128 v[202:205], v170 offset:20480
	ds_read_b128 v[206:209], v170 offset:21504
	ds_read_b128 v[210:213], v170 offset:22528
	ds_read_b128 v[214:217], v170 offset:23552
	global_load_lds_dwordx4 v[218:219], off
	s_add_i32 m0, s39, 0x2000
	s_add_u32 s92, s46, 0x40000
	v_lshl_add_u64 v[220:221], s[46:47], 0, v[130:131]
	s_addc_u32 s93, s47, 0
	s_add_i32 s38, s38, s75
	global_load_lds_dwordx4 v[220:221], off
	v_lshl_add_u64 v[222:223], s[92:93], 0, v[134:135]
	s_mov_b32 m0, s38
	v_lshl_add_u64 v[224:225], s[72:73], 0, v[132:133]
	global_load_lds_dwordx4 v[222:223], off
	v_lshl_add_u64 v[222:223], s[92:93], 0, v[130:131]
	s_add_i32 m0, s38, 0x2000
	s_nop 0
	global_load_lds_dwordx4 v[222:223], off
	v_lshl_add_u64 v[222:223], s[72:73], 0, v[136:137]
	s_mov_b32 m0, s76
	s_nop 0
	global_load_lds_dwordx4 v[222:223], off
	s_mov_b32 m0, s77
	s_nop 0
	global_load_lds_dwordx4 v[224:225], off
	s_waitcnt vmcnt(8)
	s_waitcnt lgkmcnt(0)
	s_barrier
; #define PG8_STAGE(bufoff, gbase, voff) do { _Pragma("unroll") for (int _i = 0; _i < 2; ++_i) \
;         __builtin_amdgcn_global_load_lds((const unsigned*)((const char*)(gbase) + (voff)[_i]), (PG8_LAS unsigned*)(lds + (bufoff) + ldsw + _i * 8192), 16, 0, 0); } while (0)
; #define PG8_LDA(dst, b, h) do { _Pragma("unroll") for (int m = 0; m < 4; ++m) _Pragma("unroll") for (int k = 0; k < 2; ++k) dst[m][k] = *(const PG8_LAS bf16x8*)(lds + PG8_SA(b, h) + aoff + m * 2048 + k * 1024); } while (0)
; #define PG8_LDB(dst, b, h) do { _Pragma("unroll") for (int n = 0; n < 2; ++n) _Pragma("unroll") for (int k = 0; k < 2; ++k) dst[n][k] = *(const PG8_LAS bf16x8*)(lds + PG8_SB(b, h) + boff + n * 2048 + k * 1024); } while (0)
; #define PG8_MMA(ai, bj, At, Bt) do { __builtin_amdgcn_s_setprio(1); _Pragma("unroll") for (int m = 0; m < 4; ++m) _Pragma("unroll") for (int n = 0; n < 2; ++n) _Pragma("unroll") for (int k = 0; k < 2; ++k) \
;         acc[ai][bj][m][n] = __builtin_amdgcn_mfma_f32_16x16x32_bf16(Bt[n][k], At[m][k], acc[ai][bj][m][n], 0, 0, 0); __builtin_amdgcn_s_setprio(0); } while (0)
; #define PG8_WAIT_V(n) asm volatile("s_waitcnt vmcnt(" #n ")" ::: "memory")
; #define PG8_WAIT_L(n) asm volatile("s_waitcnt lgkmcnt(" #n ")" ::: "memory")
; #define PG8_BAR __builtin_amdgcn_s_barrier()
; #define PG8_SCHED __builtin_amdgcn_sched_barrier(0)
; template <class Epi, class Sched, bool ALIGN_EPI = false, bool SP2 = false>
; __device__ __forceinline__ void gemm_phase(PG8_LAS unsigned char* lds, const Gemm g, const Sched& S, const Epi& E) {
;     ...
;             PG8_WAIT_V(8); PG8_WAIT_L(0); PG8_BAR; PG8_MMA(1, 0, At, B0); PG8_MMA(1, 1, At, B1); PG8_BAR; PG8_SCHED;
;             PG8_LDB(B0, 1, 0); PG8_LDB(B1, 1, 1); PG8_SCHED; PG8_LDA(At, 1, 0); PG8_STAGE(PG8_SA(0, 1), a2 + hstep, voffA);
;             PG8_WAIT_V(8); PG8_WAIT_L(0); PG8_BAR; PG8_MMA(0, 0, At, B0); PG8_MMA(0, 1, At, B1); PG8_BAR; PG8_SCHED;
	s_setprio 1
	s_waitcnt lgkmcnt(0)
	v_mfma_f32_16x16x32_bf16 v[58:61], v[142:145], v[180:183], v[58:61]
	v_mfma_f32_16x16x32_bf16 v[58:61], v[146:149], v[184:187], v[58:61]
	v_mfma_f32_16x16x32_bf16 v[62:65], v[150:153], v[180:183], v[62:65]
	v_mfma_f32_16x16x32_bf16 v[62:65], v[154:157], v[184:187], v[62:65]
	v_mfma_f32_16x16x32_bf16 v[50:53], v[158:161], v[180:183], v[50:53]
	v_mfma_f32_16x16x32_bf16 v[50:53], v[162:165], v[184:187], v[50:53]
	v_mfma_f32_16x16x32_bf16 v[54:57], v[172:175], v[180:183], v[54:57]
	v_mfma_f32_16x16x32_bf16 v[54:57], v[176:179], v[184:187], v[54:57]
	v_mfma_f32_16x16x32_bf16 v[42:45], v[142:145], v[188:191], v[42:45]
	v_mfma_f32_16x16x32_bf16 v[42:45], v[146:149], v[192:195], v[42:45]
	v_mfma_f32_16x16x32_bf16 v[46:49], v[150:153], v[188:191], v[46:49]
	v_mfma_f32_16x16x32_bf16 v[46:49], v[154:157], v[192:195], v[46:49]
	v_mfma_f32_16x16x32_bf16 v[34:37], v[158:161], v[188:191], v[34:37]
	v_mfma_f32_16x16x32_bf16 v[34:37], v[162:165], v[192:195], v[34:37]
	v_mfma_f32_16x16x32_bf16 v[38:41], v[172:175], v[188:191], v[38:41]
	v_mfma_f32_16x16x32_bf16 v[38:41], v[176:179], v[192:195], v[38:41]
	v_mfma_f32_16x16x32_bf16 v[26:29], v[142:145], v[202:205], v[26:29]
	v_mfma_f32_16x16x32_bf16 v[26:29], v[146:149], v[206:209], v[26:29]
	v_mfma_f32_16x16x32_bf16 v[30:33], v[150:153], v[202:205], v[30:33]
	v_mfma_f32_16x16x32_bf16 v[30:33], v[154:157], v[206:209], v[30:33]
	v_mfma_f32_16x16x32_bf16 v[18:21], v[158:161], v[202:205], v[18:21]
	v_mfma_f32_16x16x32_bf16 v[18:21], v[162:165], v[206:209], v[18:21]
	v_mfma_f32_16x16x32_bf16 v[22:25], v[172:175], v[202:205], v[22:25]
	v_mfma_f32_16x16x32_bf16 v[22:25], v[176:179], v[206:209], v[22:25]
	v_mfma_f32_16x16x32_bf16 v[10:13], v[142:145], v[210:213], v[10:13]
	v_mfma_f32_16x16x32_bf16 v[10:13], v[146:149], v[214:217], v[10:13]
	v_mfma_f32_16x16x32_bf16 v[14:17], v[150:153], v[210:213], v[14:17]
	v_mfma_f32_16x16x32_bf16 v[14:17], v[154:157], v[214:217], v[14:17]
	v_mfma_f32_16x16x32_bf16 v[2:5], v[158:161], v[210:213], v[2:5]
	v_mfma_f32_16x16x32_bf16 v[2:5], v[162:165], v[214:217], v[2:5]
	v_mfma_f32_16x16x32_bf16 v[6:9], v[172:175], v[210:213], v[6:9]
	v_mfma_f32_16x16x32_bf16 v[6:9], v[176:179], v[214:217], v[6:9]
	s_setprio 0
	s_barrier
	s_add_i32 s38, 0, 0x18000
	v_add_u32_e32 v0, s38, v167
	s_add_i32 s39, 0, 0x1c000
	ds_read_b128 v[142:145], v0
	ds_read_b128 v[146:149], v0 offset:1024
	ds_read_b128 v[150:153], v0 offset:2048
	ds_read_b128 v[154:157], v0 offset:3072
	v_add_u32_e32 v0, s39, v167
	ds_read_b128 v[158:161], v0
	ds_read_b128 v[162:165], v0 offset:1024
	ds_read_b128 v[172:175], v0 offset:2048
	ds_read_b128 v[176:179], v0 offset:3072
	s_add_u32 s72, s72, 0x40000
	s_addc_u32 s73, s73, 0
	s_mov_b32 m0, s78
	v_lshl_add_u64 v[226:227], s[72:73], 0, v[136:137]
	ds_read_b128 v[180:183], v170 offset:32768
	ds_read_b128 v[184:187], v170 offset:33792
	ds_read_b128 v[188:191], v170 offset:34816
	ds_read_b128 v[192:195], v170 offset:35840
	ds_read_b128 v[202:205], v170 offset:36864
	ds_read_b128 v[206:209], v170 offset:37888
	ds_read_b128 v[210:213], v170 offset:38912
	ds_read_b128 v[214:217], v170 offset:39936
	global_load_lds_dwordx4 v[226:227], off
	v_lshl_add_u64 v[226:227], s[72:73], 0, v[132:133]
	s_mov_b32 m0, s79
	s_nop 0
	global_load_lds_dwordx4 v[226:227], off
	s_waitcnt vmcnt(8)
	s_waitcnt lgkmcnt(0)
	s_barrier
	s_setprio 1
	s_waitcnt lgkmcnt(0)
	v_mfma_f32_16x16x32_bf16 v[122:125], v[142:145], v[180:183], v[122:125]
	v_mfma_f32_16x16x32_bf16 v[122:125], v[146:149], v[184:187], v[122:125]
	v_mfma_f32_16x16x32_bf16 v[126:129], v[150:153], v[180:183], v[126:129]
	v_mfma_f32_16x16x32_bf16 v[126:129], v[154:157], v[184:187], v[126:129]
	v_mfma_f32_16x16x32_bf16 v[114:117], v[158:161], v[180:183], v[114:117]
	v_mfma_f32_16x16x32_bf16 v[114:117], v[162:165], v[184:187], v[114:117]
	v_mfma_f32_16x16x32_bf16 v[118:121], v[172:175], v[180:183], v[118:121]
	v_mfma_f32_16x16x32_bf16 v[118:121], v[176:179], v[184:187], v[118:121]
	v_mfma_f32_16x16x32_bf16 v[106:109], v[142:145], v[188:191], v[106:109]
	v_mfma_f32_16x16x32_bf16 v[106:109], v[146:149], v[192:195], v[106:109]
	v_mfma_f32_16x16x32_bf16 v[110:113], v[150:153], v[188:191], v[110:113]
	v_mfma_f32_16x16x32_bf16 v[110:113], v[154:157], v[192:195], v[110:113]
	v_mfma_f32_16x16x32_bf16 v[98:101], v[158:161], v[188:191], v[98:101]
	v_mfma_f32_16x16x32_bf16 v[98:101], v[162:165], v[192:195], v[98:101]
	v_mfma_f32_16x16x32_bf16 v[102:105], v[172:175], v[188:191], v[102:105]
	v_mfma_f32_16x16x32_bf16 v[102:105], v[176:179], v[192:195], v[102:105]
	v_mfma_f32_16x16x32_bf16 v[90:93], v[142:145], v[202:205], v[90:93]
	v_mfma_f32_16x16x32_bf16 v[90:93], v[146:149], v[206:209], v[90:93]
	v_mfma_f32_16x16x32_bf16 v[94:97], v[150:153], v[202:205], v[94:97]
	v_mfma_f32_16x16x32_bf16 v[94:97], v[154:157], v[206:209], v[94:97]
	v_mfma_f32_16x16x32_bf16 v[82:85], v[158:161], v[202:205], v[82:85]
	v_mfma_f32_16x16x32_bf16 v[82:85], v[162:165], v[206:209], v[82:85]
	v_mfma_f32_16x16x32_bf16 v[86:89], v[172:175], v[202:205], v[86:89]
	v_mfma_f32_16x16x32_bf16 v[86:89], v[176:179], v[206:209], v[86:89]
	v_mfma_f32_16x16x32_bf16 v[74:77], v[142:145], v[210:213], v[74:77]
	v_mfma_f32_16x16x32_bf16 v[74:77], v[146:149], v[214:217], v[74:77]
	v_mfma_f32_16x16x32_bf16 v[78:81], v[150:153], v[210:213], v[78:81]
	v_mfma_f32_16x16x32_bf16 v[78:81], v[154:157], v[214:217], v[78:81]
	v_mfma_f32_16x16x32_bf16 v[66:69], v[158:161], v[210:213], v[66:69]
	v_mfma_f32_16x16x32_bf16 v[66:69], v[162:165], v[214:217], v[66:69]
	v_mfma_f32_16x16x32_bf16 v[70:73], v[172:175], v[210:213], v[70:73]
	v_mfma_f32_16x16x32_bf16 v[70:73], v[176:179], v[214:217], v[70:73]
	s_setprio 0
	s_barrier
; #define PG8_STAGE(bufoff, gbase, voff) do { _Pragma("unroll") for (int _i = 0; _i < 2; ++_i) \
;         __builtin_amdgcn_global_load_lds((const unsigned*)((const char*)(gbase) + (voff)[_i]), (PG8_LAS unsigned*)(lds + (bufoff) + ldsw + _i * 8192), 16, 0, 0); } while (0)
; #define PG8_LDA(dst, b, h) do { _Pragma("unroll") for (int m = 0; m < 4; ++m) _Pragma("unroll") for (int k = 0; k < 2; ++k) dst[m][k] = *(const PG8_LAS bf16x8*)(lds + PG8_SA(b, h) + aoff + m * 2048 + k * 1024); } while (0)
; #define PG8_MMA(ai, bj, At, Bt) do { __builtin_amdgcn_s_setprio(1); _Pragma("unroll") for (int m = 0; m < 4; ++m) _Pragma("unroll") for (int n = 0; n < 2; ++n) _Pragma("unroll") for (int k = 0; k < 2; ++k) \
;         acc[ai][bj][m][n] = __builtin_amdgcn_mfma_f32_16x16x32_bf16(Bt[n][k], At[m][k], acc[ai][bj][m][n], 0, 0, 0); __builtin_amdgcn_s_setprio(0); } while (0)
; #define PG8_WAIT_V(n) asm volatile("s_waitcnt vmcnt(" #n ")" ::: "memory")
; #define PG8_WAIT_L(n) asm volatile("s_waitcnt lgkmcnt(" #n ")" ::: "memory")
; #define PG8_BAR __builtin_amdgcn_s_barrier()
; #define PG8_SCHED __builtin_amdgcn_sched_barrier(0)
; template <class Epi, class Sched, bool ALIGN_EPI = false, bool SP2 = false>
; __device__ __forceinline__ void gemm_phase(PG8_LAS unsigned char* lds, const Gemm g, const Sched& S, const Epi& E) {
;     ...
;             PG8_LDA(At, 1, 1); PG8_STAGE(PG8_SB(1, 0), b3, voffB); PG8_STAGE(PG8_SB(1, 1), b3 + hstep, voffB); PG8_STAGE(PG8_SA(1, 0), a3, voffA);
;             PG8_WAIT_V(8); PG8_WAIT_L(0); PG8_BAR; PG8_MMA(1, 0, At, B0); PG8_MMA(1, 1, At, B1); PG8_BAR; PG8_SCHED;
;     ...
;         if constexpr (ALIGN_EPI) { if (wr == 0) PG8_BAR; }
	s_add_i32 s38, s38, s75
	v_lshl_add_u64 v[218:219], v[218:219], 0, s[30:31]
	s_mov_b32 m0, s38
	ds_read_b128 v[180:183], v170 offset:49152
	ds_read_b128 v[184:187], v170 offset:50176
	ds_read_b128 v[188:191], v170 offset:51200
	ds_read_b128 v[192:195], v170 offset:52224
	ds_read_b128 v[202:205], v170 offset:53248
	ds_read_b128 v[206:209], v170 offset:54272
	ds_read_b128 v[210:213], v170 offset:55296
	ds_read_b128 v[214:217], v170 offset:56320
	global_load_lds_dwordx4 v[218:219], off
	s_add_i32 m0, s38, 0x2000
	s_add_u32 s46, s46, 0x40080
	v_lshl_add_u64 v[218:219], v[220:221], 0, s[30:31]
	s_addc_u32 s47, s47, 0
	s_add_i32 s38, s39, s75
	global_load_lds_dwordx4 v[218:219], off
	v_lshl_add_u64 v[218:219], s[46:47], 0, v[134:135]
	s_mov_b32 m0, s38
	s_nop 0
	global_load_lds_dwordx4 v[218:219], off
	v_lshl_add_u64 v[218:219], s[46:47], 0, v[130:131]
	s_add_i32 m0, s38, 0x2000
	s_nop 0
	global_load_lds_dwordx4 v[218:219], off
	v_lshl_add_u64 v[218:219], v[222:223], 0, s[30:31]
	s_mov_b32 m0, s80
	s_nop 0
	global_load_lds_dwordx4 v[218:219], off
	v_lshl_add_u64 v[218:219], v[224:225], 0, s[30:31]
	s_mov_b32 m0, s81
	s_nop 0
	global_load_lds_dwordx4 v[218:219], off
	s_waitcnt vmcnt(8)
	s_waitcnt lgkmcnt(0)
	s_barrier
	s_setprio 1
	s_waitcnt lgkmcnt(0)
	v_mfma_f32_16x16x32_bf16 v[58:61], v[142:145], v[180:183], v[58:61]
	v_mfma_f32_16x16x32_bf16 v[58:61], v[146:149], v[184:187], v[58:61]
	v_mfma_f32_16x16x32_bf16 v[62:65], v[150:153], v[180:183], v[62:65]
	v_mfma_f32_16x16x32_bf16 v[62:65], v[154:157], v[184:187], v[62:65]
	v_mfma_f32_16x16x32_bf16 v[50:53], v[158:161], v[180:183], v[50:53]
	v_mfma_f32_16x16x32_bf16 v[50:53], v[162:165], v[184:187], v[50:53]
	v_mfma_f32_16x16x32_bf16 v[54:57], v[172:175], v[180:183], v[54:57]
	v_mfma_f32_16x16x32_bf16 v[54:57], v[176:179], v[184:187], v[54:57]
	v_mfma_f32_16x16x32_bf16 v[42:45], v[142:145], v[188:191], v[42:45]
	v_mfma_f32_16x16x32_bf16 v[42:45], v[146:149], v[192:195], v[42:45]
	v_mfma_f32_16x16x32_bf16 v[46:49], v[150:153], v[188:191], v[46:49]
	v_mfma_f32_16x16x32_bf16 v[46:49], v[154:157], v[192:195], v[46:49]
	v_mfma_f32_16x16x32_bf16 v[34:37], v[158:161], v[188:191], v[34:37]
	v_mfma_f32_16x16x32_bf16 v[34:37], v[162:165], v[192:195], v[34:37]
	v_mfma_f32_16x16x32_bf16 v[38:41], v[172:175], v[188:191], v[38:41]
	v_mfma_f32_16x16x32_bf16 v[38:41], v[176:179], v[192:195], v[38:41]
	v_mfma_f32_16x16x32_bf16 v[26:29], v[142:145], v[202:205], v[26:29]
	v_mfma_f32_16x16x32_bf16 v[26:29], v[146:149], v[206:209], v[26:29]
	v_mfma_f32_16x16x32_bf16 v[30:33], v[150:153], v[202:205], v[30:33]
	v_mfma_f32_16x16x32_bf16 v[30:33], v[154:157], v[206:209], v[30:33]
	v_mfma_f32_16x16x32_bf16 v[18:21], v[158:161], v[202:205], v[18:21]
	v_mfma_f32_16x16x32_bf16 v[18:21], v[162:165], v[206:209], v[18:21]
	v_mfma_f32_16x16x32_bf16 v[22:25], v[172:175], v[202:205], v[22:25]
	v_mfma_f32_16x16x32_bf16 v[22:25], v[176:179], v[206:209], v[22:25]
	v_mfma_f32_16x16x32_bf16 v[10:13], v[142:145], v[210:213], v[10:13]
	v_mfma_f32_16x16x32_bf16 v[10:13], v[146:149], v[214:217], v[10:13]
	v_mfma_f32_16x16x32_bf16 v[14:17], v[150:153], v[210:213], v[14:17]
	v_mfma_f32_16x16x32_bf16 v[14:17], v[154:157], v[214:217], v[14:17]
	v_mfma_f32_16x16x32_bf16 v[2:5], v[158:161], v[210:213], v[2:5]
	v_mfma_f32_16x16x32_bf16 v[2:5], v[162:165], v[214:217], v[2:5]
	v_mfma_f32_16x16x32_bf16 v[6:9], v[172:175], v[210:213], v[6:9]
	v_mfma_f32_16x16x32_bf16 v[6:9], v[176:179], v[214:217], v[6:9]
	s_setprio 0
	s_barrier
	s_add_i32 s84, s84, 2
	s_add_u32 s48, s48, 0x100
	s_addc_u32 s49, s49, 0
	s_add_u32 s53, s53, 0x100
	s_addc_u32 s69, s69, 0
	s_cmp_gt_u32 s84, 13
	s_cbranch_scc0 .LBB0_408
	s_and_b64 vcc, exec, s[64:65]
	s_cbranch_vccz .LBB0_411
	s_barrier
